# baseline (speedup 1.0000x reference)
; #define LDA(dst, b, h) for (int m = 0; m < 4; ++m) for (int k = 0; k < 2; ++k) \
;     dst[m][k] = *reinterpret_cast<const bf16x8*>((char*)SA(b, h) + lds_byte(wr * 64 + m * 16 + fr, k * 32 + fq * 8))
; #define LDB(dst, b, h) for (int n = 0; n < 2; ++n) for (int k = 0; k < 2; ++k) \
;     dst[n][k] = *reinterpret_cast<const bf16x8*>((char*)SB(b, h) + lds_byte(wc * 32 + n * 16 + fr, k * 32 + fq * 8))
; #define MMA(ai, bj, At, Bt_) do { __builtin_amdgcn_s_setprio(1); \
;     for (int m = 0; m < 4; ++m) for (int n = 0; n < 2; ++n) for (int k = 0; k < 2; ++k) \
;       acc[ai][bj][m][n] = __builtin_amdgcn_mfma_f32_16x16x32_bf16(At[m][k], Bt_[n][k], acc[ai][bj][m][n], 0, 0, 0); \
;     __builtin_amdgcn_s_setprio(0); } while (0)
; #define WAIT_L(n) asm volatile("s_waitcnt lgkmcnt(" #n ")" ::: "memory")
; #define BAR __builtin_amdgcn_s_barrier()
; #define SCHED __builtin_amdgcn_sched_barrier(0)
;     ...
;       LDB(B0, 0, 0); SCHED; LDA(At, 0, 0); STAGE(SA(1, 1), A, brow + HALF, t + 1);
;       WAIT_L(8); BAR; WAIT_L(0); MMA(0, 0, At, B0); BAR; SCHED;
;       LDB(B1, 0, 1); STAGE(SB(0, 0), Bt, bcol, t + 2);
;       BAR; WAIT_L(0); MMA(0, 1, At, B1); BAR;
;       LDA(At, 0, 1); STAGE(SA(0, 0), A, brow, t + 2);
;       BAR; WAIT_L(0); MMA(1, 0, At, B0); BAR; SCHED;
.LBB0_98:
	v_add_u32_e32 v143, s2, v142
	ds_read_b128 v[146:149], v143
	ds_read_b128 v[150:153], v143 offset:1024
	ds_read_b128 v[154:157], v143 offset:2048
	ds_read_b128 v[158:161], v143 offset:3072
	s_add_u32 s66, s55, s4
	s_addc_u32 s67, s57, s5
	s_add_i32 s63, s15, 0xc000
	ds_read_b128 v[162:165], v133
	ds_read_b128 v[184:187], v133 offset:1024
	ds_read_b128 v[188:191], v134
	ds_read_b128 v[192:195], v134 offset:1024
	ds_read_b128 v[196:199], v137
	ds_read_b128 v[200:203], v137 offset:1024
	ds_read_b128 v[204:207], v139
	ds_read_b128 v[208:211], v139 offset:1024
	s_mov_b32 m0, s63
	v_lshl_add_u64 v[144:145], s[66:67], 0, v[0:1]
	s_add_i32 s59, s15, 0xe000
	global_load_lds_dwordx4 v[144:145], off
	v_lshl_add_u64 v[144:145], s[66:67], 0, v[140:141]
	s_mov_b32 m0, s59
	s_nop 0
	global_load_lds_dwordx4 v[144:145], off
	s_waitcnt lgkmcnt(8)
	s_barrier
	s_waitcnt lgkmcnt(0)
	s_setprio 0
	s_waitcnt lgkmcnt(0)
	v_mfma_f32_16x16x32_bf16 v[126:129], v[162:165], v[146:149], v[126:129]
	v_mfma_f32_16x16x32_bf16 v[122:125], v[162:165], v[154:157], v[122:125]
	v_mfma_f32_16x16x32_bf16 v[118:121], v[188:191], v[146:149], v[118:121]
	v_mfma_f32_16x16x32_bf16 v[114:117], v[188:191], v[154:157], v[114:117]
	v_mfma_f32_16x16x32_bf16 v[110:113], v[196:199], v[146:149], v[110:113]
	v_mfma_f32_16x16x32_bf16 v[106:109], v[196:199], v[154:157], v[106:109]
	v_mfma_f32_16x16x32_bf16 v[102:105], v[204:207], v[146:149], v[102:105]
	v_mfma_f32_16x16x32_bf16 v[98:101], v[204:207], v[154:157], v[98:101]
	v_mfma_f32_16x16x32_bf16 v[126:129], v[184:187], v[150:153], v[126:129]
	v_mfma_f32_16x16x32_bf16 v[122:125], v[184:187], v[158:161], v[122:125]
	v_mfma_f32_16x16x32_bf16 v[118:121], v[192:195], v[150:153], v[118:121]
	v_mfma_f32_16x16x32_bf16 v[114:117], v[192:195], v[158:161], v[114:117]
	v_mfma_f32_16x16x32_bf16 v[110:113], v[200:203], v[150:153], v[110:113]
	v_mfma_f32_16x16x32_bf16 v[106:109], v[200:203], v[158:161], v[106:109]
	v_mfma_f32_16x16x32_bf16 v[102:105], v[208:211], v[150:153], v[102:105]
	v_mfma_f32_16x16x32_bf16 v[98:101], v[208:211], v[158:161], v[98:101]
	s_setprio 1
	s_barrier
	s_add_i32 s58, s58, 2
	s_add_u32 s65, s50, s4
	s_addc_u32 s70, s51, s5
	s_add_u32 s66, s65, 0x100
	v_add_u32_e32 v144, s76, v142
	s_addc_u32 s67, s70, 0
	s_mov_b32 m0, s16
	ds_read_b128 v[212:215], v144
	ds_read_b128 v[216:219], v144 offset:1024
	ds_read_b128 v[220:223], v144 offset:2048
	ds_read_b128 v[224:227], v144 offset:3072
	s_nop 0
	v_lshl_add_u64 v[166:167], s[66:67], 0, v[0:1]
	global_load_lds_dwordx4 v[166:167], off
	v_lshl_add_u64 v[166:167], s[66:67], 0, v[140:141]
	s_mov_b32 m0, s17
	s_nop 0
	global_load_lds_dwordx4 v[166:167], off
	s_barrier
	s_waitcnt lgkmcnt(0)
	s_setprio 0
	s_waitcnt lgkmcnt(0)
	v_mfma_f32_16x16x32_bf16 v[94:97], v[162:165], v[212:215], v[94:97]
	v_mfma_f32_16x16x32_bf16 v[90:93], v[162:165], v[220:223], v[90:93]
	v_mfma_f32_16x16x32_bf16 v[86:89], v[188:191], v[212:215], v[86:89]
	v_mfma_f32_16x16x32_bf16 v[82:85], v[188:191], v[220:223], v[82:85]
	v_mfma_f32_16x16x32_bf16 v[78:81], v[196:199], v[212:215], v[78:81]
	v_mfma_f32_16x16x32_bf16 v[74:77], v[196:199], v[220:223], v[74:77]
	v_mfma_f32_16x16x32_bf16 v[70:73], v[204:207], v[212:215], v[70:73]
	v_mfma_f32_16x16x32_bf16 v[66:69], v[204:207], v[220:223], v[66:69]
	v_mfma_f32_16x16x32_bf16 v[94:97], v[184:187], v[216:219], v[94:97]
	v_mfma_f32_16x16x32_bf16 v[90:93], v[184:187], v[224:227], v[90:93]
	v_mfma_f32_16x16x32_bf16 v[86:89], v[192:195], v[216:219], v[86:89]
	v_mfma_f32_16x16x32_bf16 v[82:85], v[192:195], v[224:227], v[82:85]
	v_mfma_f32_16x16x32_bf16 v[78:81], v[200:203], v[216:219], v[78:81]
	v_mfma_f32_16x16x32_bf16 v[74:77], v[200:203], v[224:227], v[74:77]
	v_mfma_f32_16x16x32_bf16 v[70:73], v[208:211], v[216:219], v[70:73]
	v_mfma_f32_16x16x32_bf16 v[66:69], v[208:211], v[224:227], v[66:69]
	s_setprio 1
	s_add_u32 s71, s44, s4
	s_addc_u32 s72, s45, s5
	s_add_u32 s66, s71, 0x100
	s_addc_u32 s67, s72, 0
	s_mov_b32 m0, s15
	s_barrier
	ds_read_b128 v[162:165], v133 offset:16384
	ds_read_b128 v[184:187], v133 offset:17408
	ds_read_b128 v[188:191], v134 offset:16384
	ds_read_b128 v[192:195], v134 offset:17408
	ds_read_b128 v[196:199], v137 offset:16384
	ds_read_b128 v[200:203], v137 offset:17408
	ds_read_b128 v[204:207], v139 offset:16384
	ds_read_b128 v[208:211], v139 offset:17408
	s_nop 0
	v_lshl_add_u64 v[166:167], s[66:67], 0, v[0:1]
	global_load_lds_dwordx4 v[166:167], off
	v_lshl_add_u64 v[166:167], s[66:67], 0, v[140:141]
	s_mov_b32 m0, s18
	s_nop 0
	global_load_lds_dwordx4 v[166:167], off
	s_barrier
	s_waitcnt lgkmcnt(0)
	s_setprio 0
	s_waitcnt lgkmcnt(0)
	v_mfma_f32_16x16x32_bf16 v[62:65], v[162:165], v[146:149], v[62:65]
	v_mfma_f32_16x16x32_bf16 v[58:61], v[162:165], v[154:157], v[58:61]
	v_mfma_f32_16x16x32_bf16 v[54:57], v[188:191], v[146:149], v[54:57]
	v_mfma_f32_16x16x32_bf16 v[50:53], v[188:191], v[154:157], v[50:53]
	v_mfma_f32_16x16x32_bf16 v[46:49], v[196:199], v[146:149], v[46:49]
	v_mfma_f32_16x16x32_bf16 v[42:45], v[196:199], v[154:157], v[42:45]
	v_mfma_f32_16x16x32_bf16 v[38:41], v[204:207], v[146:149], v[38:41]
	v_mfma_f32_16x16x32_bf16 v[34:37], v[204:207], v[154:157], v[34:37]
	v_mfma_f32_16x16x32_bf16 v[62:65], v[184:187], v[150:153], v[62:65]
	v_mfma_f32_16x16x32_bf16 v[58:61], v[184:187], v[158:161], v[58:61]
	v_mfma_f32_16x16x32_bf16 v[54:57], v[192:195], v[150:153], v[54:57]
	v_mfma_f32_16x16x32_bf16 v[50:53], v[192:195], v[158:161], v[50:53]
	v_mfma_f32_16x16x32_bf16 v[46:49], v[200:203], v[150:153], v[46:49]
	v_mfma_f32_16x16x32_bf16 v[42:45], v[200:203], v[158:161], v[42:45]
	v_mfma_f32_16x16x32_bf16 v[38:41], v[208:211], v[150:153], v[38:41]
	v_mfma_f32_16x16x32_bf16 v[34:37], v[208:211], v[158:161], v[34:37]
	s_setprio 1
	s_barrier
; #define LDA(dst, b, h) for (int m = 0; m < 4; ++m) for (int k = 0; k < 2; ++k) \
;     dst[m][k] = *reinterpret_cast<const bf16x8*>((char*)SA(b, h) + lds_byte(wr * 64 + m * 16 + fr, k * 32 + fq * 8))
; #define LDB(dst, b, h) for (int n = 0; n < 2; ++n) for (int k = 0; k < 2; ++k) \
;     dst[n][k] = *reinterpret_cast<const bf16x8*>((char*)SB(b, h) + lds_byte(wc * 32 + n * 16 + fr, k * 32 + fq * 8))
; #define MMA(ai, bj, At, Bt_) do { __builtin_amdgcn_s_setprio(1); \
;     for (int m = 0; m < 4; ++m) for (int n = 0; n < 2; ++n) for (int k = 0; k < 2; ++k) \
;       acc[ai][bj][m][n] = __builtin_amdgcn_mfma_f32_16x16x32_bf16(At[m][k], Bt_[n][k], acc[ai][bj][m][n], 0, 0, 0); \
;     __builtin_amdgcn_s_setprio(0); } while (0)
; #define WAIT_V(n) asm volatile("s_waitcnt vmcnt(" #n ")" ::: "memory")
; #define WAIT_L(n) asm volatile("s_waitcnt lgkmcnt(" #n ")" ::: "memory")
; #define BAR __builtin_amdgcn_s_barrier()
; #define SCHED __builtin_amdgcn_sched_barrier(0)
;     ...
;       STAGE(SB(0, 1), Bt, bcol + HALF, t + 2);
;       WAIT_V(6); BAR; MMA(1, 1, At, B1); BAR;
;       LDB(B0, 1, 0); SCHED; LDA(At, 1, 0); STAGE(SA(0, 1), A, brow + HALF, t + 2);
;       WAIT_L(8); BAR; WAIT_L(0); MMA(0, 0, At, B0); BAR; SCHED;
;       LDB(B1, 1, 1); STAGE(SB(1, 0), Bt, bcol, t + 3);
;       BAR; WAIT_L(0); MMA(0, 1, At, B1); BAR;
	s_add_u32 s73, s6, s4
	s_addc_u32 s82, s7, s5
	s_add_u32 s66, s73, 0x160100
	s_addc_u32 s67, s82, 0
	s_mov_b32 m0, s19
	s_nop 0
	v_lshl_add_u64 v[146:147], s[66:67], 0, v[0:1]
	global_load_lds_dwordx4 v[146:147], off
	v_lshl_add_u64 v[146:147], s[66:67], 0, v[140:141]
	s_mov_b32 m0, s21
	s_nop 0
	global_load_lds_dwordx4 v[146:147], off
	s_waitcnt vmcnt(6)
	s_barrier
	s_setprio 0
	v_mfma_f32_16x16x32_bf16 v[30:33], v[162:165], v[212:215], v[30:33]
	v_mfma_f32_16x16x32_bf16 v[26:29], v[162:165], v[220:223], v[26:29]
	v_mfma_f32_16x16x32_bf16 v[22:25], v[188:191], v[212:215], v[22:25]
	v_mfma_f32_16x16x32_bf16 v[18:21], v[188:191], v[220:223], v[18:21]
	v_mfma_f32_16x16x32_bf16 v[14:17], v[196:199], v[212:215], v[14:17]
	v_mfma_f32_16x16x32_bf16 v[10:13], v[196:199], v[220:223], v[10:13]
	v_mfma_f32_16x16x32_bf16 v[6:9], v[204:207], v[212:215], v[6:9]
	v_mfma_f32_16x16x32_bf16 v[2:5], v[204:207], v[220:223], v[2:5]
	v_mfma_f32_16x16x32_bf16 v[30:33], v[184:187], v[216:219], v[30:33]
	v_mfma_f32_16x16x32_bf16 v[26:29], v[184:187], v[224:227], v[26:29]
	v_mfma_f32_16x16x32_bf16 v[22:25], v[192:195], v[216:219], v[22:25]
	v_mfma_f32_16x16x32_bf16 v[18:21], v[192:195], v[224:227], v[18:21]
	v_mfma_f32_16x16x32_bf16 v[14:17], v[200:203], v[216:219], v[14:17]
	v_mfma_f32_16x16x32_bf16 v[10:13], v[200:203], v[224:227], v[10:13]
	v_mfma_f32_16x16x32_bf16 v[6:9], v[208:211], v[216:219], v[6:9]
	v_mfma_f32_16x16x32_bf16 v[2:5], v[208:211], v[224:227], v[2:5]
	s_setprio 1
	v_add_u32_e32 v145, s77, v142
	s_barrier
	ds_read_b128 v[148:151], v145
	ds_read_b128 v[152:155], v145 offset:1024
	ds_read_b128 v[156:159], v145 offset:2048
	ds_read_b128 v[160:163], v145 offset:3072
	s_add_u32 s66, s71, 0x160100
	s_addc_u32 s67, s72, 0
	s_mov_b32 m0, s30
	ds_read_b128 v[164:167], v133 offset:32768
	ds_read_b128 v[184:187], v133 offset:33792
	ds_read_b128 v[188:191], v134 offset:32768
	ds_read_b128 v[192:195], v134 offset:33792
	ds_read_b128 v[196:199], v137 offset:32768
	ds_read_b128 v[200:203], v137 offset:33792
	ds_read_b128 v[204:207], v139 offset:32768
	ds_read_b128 v[208:211], v139 offset:33792
	s_nop 0
	v_lshl_add_u64 v[146:147], s[66:67], 0, v[0:1]
	global_load_lds_dwordx4 v[146:147], off
	v_lshl_add_u64 v[146:147], s[66:67], 0, v[140:141]
	s_mov_b32 m0, s31
	s_nop 0
	global_load_lds_dwordx4 v[146:147], off
	s_waitcnt lgkmcnt(8)
	s_barrier
	s_waitcnt lgkmcnt(0)
	s_setprio 0
	s_waitcnt lgkmcnt(0)
	v_mfma_f32_16x16x32_bf16 v[126:129], v[164:167], v[148:151], v[126:129]
	v_mfma_f32_16x16x32_bf16 v[122:125], v[164:167], v[156:159], v[122:125]
	v_mfma_f32_16x16x32_bf16 v[118:121], v[188:191], v[148:151], v[118:121]
	v_mfma_f32_16x16x32_bf16 v[114:117], v[188:191], v[156:159], v[114:117]
	v_mfma_f32_16x16x32_bf16 v[110:113], v[196:199], v[148:151], v[110:113]
	v_mfma_f32_16x16x32_bf16 v[106:109], v[196:199], v[156:159], v[106:109]
	v_mfma_f32_16x16x32_bf16 v[102:105], v[204:207], v[148:151], v[102:105]
	v_mfma_f32_16x16x32_bf16 v[98:101], v[204:207], v[156:159], v[98:101]
	v_mfma_f32_16x16x32_bf16 v[126:129], v[184:187], v[152:155], v[126:129]
	v_mfma_f32_16x16x32_bf16 v[122:125], v[184:187], v[160:163], v[122:125]
	v_mfma_f32_16x16x32_bf16 v[118:121], v[192:195], v[152:155], v[118:121]
	v_mfma_f32_16x16x32_bf16 v[114:117], v[192:195], v[160:163], v[114:117]
	v_mfma_f32_16x16x32_bf16 v[110:113], v[200:203], v[152:155], v[110:113]
	v_mfma_f32_16x16x32_bf16 v[106:109], v[200:203], v[160:163], v[106:109]
	v_mfma_f32_16x16x32_bf16 v[102:105], v[208:211], v[152:155], v[102:105]
	v_mfma_f32_16x16x32_bf16 v[98:101], v[208:211], v[160:163], v[98:101]
	s_setprio 1
	s_barrier
	s_add_u32 s66, s65, 0x180
	v_add_u32_e32 v146, s78, v142
	s_addc_u32 s67, s70, 0
	s_mov_b32 m0, s34
	ds_read_b128 v[212:215], v146
	ds_read_b128 v[216:219], v146 offset:1024
	ds_read_b128 v[220:223], v146 offset:2048
	ds_read_b128 v[224:227], v146 offset:3072
	s_nop 0
	v_lshl_add_u64 v[228:229], s[66:67], 0, v[0:1]
	global_load_lds_dwordx4 v[228:229], off
	v_lshl_add_u64 v[228:229], s[66:67], 0, v[140:141]
	s_mov_b32 m0, s35
	s_nop 0
	global_load_lds_dwordx4 v[228:229], off
	s_barrier
	s_waitcnt lgkmcnt(0)
	s_setprio 0
	s_waitcnt lgkmcnt(0)
	v_mfma_f32_16x16x32_bf16 v[94:97], v[164:167], v[212:215], v[94:97]
	v_mfma_f32_16x16x32_bf16 v[90:93], v[164:167], v[220:223], v[90:93]
	v_mfma_f32_16x16x32_bf16 v[86:89], v[188:191], v[212:215], v[86:89]
	v_mfma_f32_16x16x32_bf16 v[82:85], v[188:191], v[220:223], v[82:85]
	v_mfma_f32_16x16x32_bf16 v[78:81], v[196:199], v[212:215], v[78:81]
	v_mfma_f32_16x16x32_bf16 v[74:77], v[196:199], v[220:223], v[74:77]
	v_mfma_f32_16x16x32_bf16 v[70:73], v[204:207], v[212:215], v[70:73]
	v_mfma_f32_16x16x32_bf16 v[66:69], v[204:207], v[220:223], v[66:69]
	v_mfma_f32_16x16x32_bf16 v[94:97], v[184:187], v[216:219], v[94:97]
	v_mfma_f32_16x16x32_bf16 v[90:93], v[184:187], v[224:227], v[90:93]
	v_mfma_f32_16x16x32_bf16 v[86:89], v[192:195], v[216:219], v[86:89]
	v_mfma_f32_16x16x32_bf16 v[82:85], v[192:195], v[224:227], v[82:85]
	v_mfma_f32_16x16x32_bf16 v[78:81], v[200:203], v[216:219], v[78:81]
	v_mfma_f32_16x16x32_bf16 v[74:77], v[200:203], v[224:227], v[74:77]
	v_mfma_f32_16x16x32_bf16 v[70:73], v[208:211], v[216:219], v[70:73]
	v_mfma_f32_16x16x32_bf16 v[66:69], v[208:211], v[224:227], v[66:69]
	s_setprio 1
	s_add_u32 s66, s71, 0x180
	s_addc_u32 s67, s72, 0
	s_mov_b32 m0, s37
	s_barrier
; #define LDA(dst, b, h) for (int m = 0; m < 4; ++m) for (int k = 0; k < 2; ++k) \
;     dst[m][k] = *reinterpret_cast<const bf16x8*>((char*)SA(b, h) + lds_byte(wr * 64 + m * 16 + fr, k * 32 + fq * 8))
; #define LDB(dst, b, h) for (int n = 0; n < 2; ++n) for (int k = 0; k < 2; ++k) \
;     dst[n][k] = *reinterpret_cast<const bf16x8*>((char*)SB(b, h) + lds_byte(wc * 32 + n * 16 + fr, k * 32 + fq * 8))
; #define MMA(ai, bj, At, Bt_) do { __builtin_amdgcn_s_setprio(1); \
;     for (int m = 0; m < 4; ++m) for (int n = 0; n < 2; ++n) for (int k = 0; k < 2; ++k) \
;       acc[ai][bj][m][n] = __builtin_amdgcn_mfma_f32_16x16x32_bf16(At[m][k], Bt_[n][k], acc[ai][bj][m][n], 0, 0, 0); \
;     __builtin_amdgcn_s_setprio(0); } while (0)
; #define WAIT_V(n) asm volatile("s_waitcnt vmcnt(" #n ")" ::: "memory")
; #define WAIT_L(n) asm volatile("s_waitcnt lgkmcnt(" #n ")" ::: "memory")
; #define BAR __builtin_amdgcn_s_barrier()
; #define SCHED __builtin_amdgcn_sched_barrier(0)
;     ...
;       LDA(At, 1, 1); STAGE(SA(1, 0), A, brow, t + 3);
;       BAR; WAIT_L(0); MMA(1, 0, At, B0); BAR; SCHED;
;       STAGE(SB(1, 1), Bt, bcol + HALF, t + 3);
;       WAIT_V(6); BAR; MMA(1, 1, At, B1); BAR;
;     }
;     { LDB(B0, 0, 0); LDA(At, 0, 0); STAGE(SA(1, 1), A, brow + HALF, nt - 1);
;       BAR; WAIT_L(0); MMA(0, 0, At, B0); BAR;
	ds_read_b128 v[164:167], v133 offset:49152
	ds_read_b128 v[184:187], v133 offset:50176
	ds_read_b128 v[188:191], v134 offset:49152
	ds_read_b128 v[192:195], v134 offset:50176
	ds_read_b128 v[196:199], v137 offset:49152
	ds_read_b128 v[200:203], v137 offset:50176
	ds_read_b128 v[204:207], v139 offset:49152
	ds_read_b128 v[208:211], v139 offset:50176
	s_nop 0
	v_lshl_add_u64 v[228:229], s[66:67], 0, v[0:1]
	global_load_lds_dwordx4 v[228:229], off
	v_lshl_add_u64 v[228:229], s[66:67], 0, v[140:141]
	s_mov_b32 m0, s38
	s_nop 0
	global_load_lds_dwordx4 v[228:229], off
	s_barrier
	s_waitcnt lgkmcnt(0)
	s_setprio 0
	s_waitcnt lgkmcnt(0)
	v_mfma_f32_16x16x32_bf16 v[62:65], v[164:167], v[148:151], v[62:65]
	v_mfma_f32_16x16x32_bf16 v[58:61], v[164:167], v[156:159], v[58:61]
	v_mfma_f32_16x16x32_bf16 v[54:57], v[188:191], v[148:151], v[54:57]
	v_mfma_f32_16x16x32_bf16 v[50:53], v[188:191], v[156:159], v[50:53]
	v_mfma_f32_16x16x32_bf16 v[46:49], v[196:199], v[148:151], v[46:49]
	v_mfma_f32_16x16x32_bf16 v[42:45], v[196:199], v[156:159], v[42:45]
	v_mfma_f32_16x16x32_bf16 v[38:41], v[204:207], v[148:151], v[38:41]
	v_mfma_f32_16x16x32_bf16 v[34:37], v[204:207], v[156:159], v[34:37]
	v_mfma_f32_16x16x32_bf16 v[62:65], v[184:187], v[152:155], v[62:65]
	v_mfma_f32_16x16x32_bf16 v[58:61], v[184:187], v[160:163], v[58:61]
	v_mfma_f32_16x16x32_bf16 v[54:57], v[192:195], v[152:155], v[54:57]
	v_mfma_f32_16x16x32_bf16 v[50:53], v[192:195], v[160:163], v[50:53]
	v_mfma_f32_16x16x32_bf16 v[46:49], v[200:203], v[152:155], v[46:49]
	v_mfma_f32_16x16x32_bf16 v[42:45], v[200:203], v[160:163], v[42:45]
	v_mfma_f32_16x16x32_bf16 v[38:41], v[208:211], v[152:155], v[38:41]
	v_mfma_f32_16x16x32_bf16 v[34:37], v[208:211], v[160:163], v[34:37]
	s_setprio 1
	s_barrier
	s_add_u32 s66, s73, 0x160180
	s_addc_u32 s67, s82, 0
	s_mov_b32 m0, s41
	s_nop 0
	v_lshl_add_u64 v[148:149], s[66:67], 0, v[0:1]
	global_load_lds_dwordx4 v[148:149], off
	v_lshl_add_u64 v[148:149], s[66:67], 0, v[140:141]
	s_mov_b32 m0, s42
	s_nop 0
	global_load_lds_dwordx4 v[148:149], off
	s_waitcnt vmcnt(6)
	s_barrier
	s_setprio 0
	v_mfma_f32_16x16x32_bf16 v[30:33], v[164:167], v[212:215], v[30:33]
	v_mfma_f32_16x16x32_bf16 v[26:29], v[164:167], v[220:223], v[26:29]
	v_mfma_f32_16x16x32_bf16 v[22:25], v[188:191], v[212:215], v[22:25]
	v_mfma_f32_16x16x32_bf16 v[18:21], v[188:191], v[220:223], v[18:21]
	v_mfma_f32_16x16x32_bf16 v[14:17], v[196:199], v[212:215], v[14:17]
	v_mfma_f32_16x16x32_bf16 v[10:13], v[196:199], v[220:223], v[10:13]
	v_mfma_f32_16x16x32_bf16 v[6:9], v[204:207], v[212:215], v[6:9]
	v_mfma_f32_16x16x32_bf16 v[2:5], v[204:207], v[220:223], v[2:5]
	v_mfma_f32_16x16x32_bf16 v[30:33], v[184:187], v[216:219], v[30:33]
	v_mfma_f32_16x16x32_bf16 v[26:29], v[184:187], v[224:227], v[26:29]
	v_mfma_f32_16x16x32_bf16 v[22:25], v[192:195], v[216:219], v[22:25]
	v_mfma_f32_16x16x32_bf16 v[18:21], v[192:195], v[224:227], v[18:21]
	v_mfma_f32_16x16x32_bf16 v[14:17], v[200:203], v[216:219], v[14:17]
	v_mfma_f32_16x16x32_bf16 v[10:13], v[200:203], v[224:227], v[10:13]
	v_mfma_f32_16x16x32_bf16 v[6:9], v[208:211], v[216:219], v[6:9]
	v_mfma_f32_16x16x32_bf16 v[2:5], v[208:211], v[224:227], v[2:5]
	s_setprio 1
	s_add_u32 s6, s6, 0x100
	s_addc_u32 s7, s7, 0
	s_add_u32 s44, s44, 0x100
	s_addc_u32 s45, s45, 0
	s_add_u32 s50, s50, 0x100
	s_addc_u32 s51, s51, 0
	s_add_u32 s55, s55, 0x100
	s_addc_u32 s57, s57, 0
	s_cmp_ge_u32 s58, s43
	s_barrier
	s_cbranch_scc0 .LBB0_98
	s_setprio 0
	s_add_i32 s4, s48, s14
	s_add_i32 s48, s4, -1
	s_lshl_b64 s[4:5], s[48:49], 7
	s_add_u32 s4, s22, s4
	s_addc_u32 s5, s23, s5
	s_add_u32 s4, s4, s40
	s_addc_u32 s5, s5, s39
	s_mov_b32 m0, s63
	ds_read_b128 v[148:151], v143
	ds_read_b128 v[152:155], v143 offset:1024
	ds_read_b128 v[156:159], v143 offset:2048
	ds_read_b128 v[160:163], v143 offset:3072
	ds_read_b128 v[164:167], v133
	ds_read_b128 v[184:187], v133 offset:1024
	ds_read_b128 v[188:191], v134
	ds_read_b128 v[192:195], v134 offset:1024
	ds_read_b128 v[196:199], v137
	ds_read_b128 v[200:203], v137 offset:1024
	ds_read_b128 v[204:207], v139
	ds_read_b128 v[208:211], v139 offset:1024
	s_nop 0
	v_lshl_add_u64 v[142:143], s[4:5], 0, v[0:1]
	global_load_lds_dwordx4 v[142:143], off
	v_lshl_add_u64 v[140:141], s[4:5], 0, v[140:141]
	s_mov_b32 m0, s59
	s_nop 0
	global_load_lds_dwordx4 v[140:141], off
	s_barrier
	s_waitcnt lgkmcnt(0)
	s_setprio 1
	s_waitcnt lgkmcnt(0)
	v_mfma_f32_16x16x32_bf16 v[126:129], v[164:167], v[148:151], v[126:129]
	v_mfma_f32_16x16x32_bf16 v[122:125], v[164:167], v[156:159], v[122:125]
	v_mfma_f32_16x16x32_bf16 v[118:121], v[188:191], v[148:151], v[118:121]
	v_mfma_f32_16x16x32_bf16 v[110:113], v[196:199], v[148:151], v[110:113]
	v_mfma_f32_16x16x32_bf16 v[106:109], v[196:199], v[156:159], v[106:109]
	v_mfma_f32_16x16x32_bf16 v[102:105], v[204:207], v[148:151], v[102:105]
	v_mfma_f32_16x16x32_bf16 v[98:101], v[204:207], v[156:159], v[98:101]
	v_mfma_f32_16x16x32_bf16 v[126:129], v[184:187], v[152:155], v[126:129]
	v_mfma_f32_16x16x32_bf16 v[122:125], v[184:187], v[160:163], v[122:125]
	v_mfma_f32_16x16x32_bf16 v[118:121], v[192:195], v[152:155], v[118:121]
	v_mfma_f32_16x16x32_bf16 v[114:117], v[188:191], v[156:159], v[114:117]
	v_mfma_f32_16x16x32_bf16 v[110:113], v[200:203], v[152:155], v[110:113]
	v_mfma_f32_16x16x32_bf16 v[106:109], v[200:203], v[160:163], v[106:109]
	v_mfma_f32_16x16x32_bf16 v[102:105], v[208:211], v[152:155], v[102:105]
	v_mfma_f32_16x16x32_bf16 v[98:101], v[208:211], v[160:163], v[98:101]
	v_mfma_f32_16x16x32_bf16 v[140:143], v[192:195], v[160:163], v[114:117]
	s_setprio 0
	s_barrier
; #define LDA(dst, b, h) for (int m = 0; m < 4; ++m) for (int k = 0; k < 2; ++k) \
;     dst[m][k] = *reinterpret_cast<const bf16x8*>((char*)SA(b, h) + lds_byte(wr * 64 + m * 16 + fr, k * 32 + fq * 8))
; #define LDB(dst, b, h) for (int n = 0; n < 2; ++n) for (int k = 0; k < 2; ++k) \
;     dst[n][k] = *reinterpret_cast<const bf16x8*>((char*)SB(b, h) + lds_byte(wc * 32 + n * 16 + fr, k * 32 + fq * 8))
; #define MMA(ai, bj, At, Bt_) do { __builtin_amdgcn_s_setprio(1); \
;     for (int m = 0; m < 4; ++m) for (int n = 0; n < 2; ++n) for (int k = 0; k < 2; ++k) \
;       acc[ai][bj][m][n] = __builtin_amdgcn_mfma_f32_16x16x32_bf16(At[m][k], Bt_[n][k], acc[ai][bj][m][n], 0, 0, 0); \
;     __builtin_amdgcn_s_setprio(0); } while (0)
; #define WAIT_V(n) asm volatile("s_waitcnt vmcnt(" #n ")" ::: "memory")
; #define WAIT_L(n) asm volatile("s_waitcnt lgkmcnt(" #n ")" ::: "memory")
; #define BAR __builtin_amdgcn_s_barrier()
;     ...
;       LDB(B1, 0, 1); BAR; WAIT_L(0); MMA(0, 1, At, B1); BAR;
;       LDA(At, 0, 1); WAIT_V(4); BAR; WAIT_L(0); MMA(1, 0, At, B0); MMA(1, 1, At, B1); BAR; }
;     { LDB(B0, 1, 0); LDA(At, 1, 0); WAIT_V(2); BAR; WAIT_L(0); MMA(0, 0, At, B0); BAR;
	s_nop 0
	ds_read_b128 v[114:117], v144
	ds_read_b128 v[212:215], v144 offset:1024
	ds_read_b128 v[216:219], v144 offset:2048
	ds_read_b128 v[220:223], v144 offset:3072
	s_barrier
	s_waitcnt lgkmcnt(0)
	s_setprio 1
	s_waitcnt lgkmcnt(0)
	v_mfma_f32_16x16x32_bf16 v[90:93], v[164:167], v[216:219], v[90:93]
	v_mfma_f32_16x16x32_bf16 v[86:89], v[188:191], v[114:117], v[86:89]
	v_mfma_f32_16x16x32_bf16 v[94:97], v[164:167], v[114:117], v[94:97]
	v_mfma_f32_16x16x32_bf16 v[90:93], v[184:187], v[220:223], v[90:93]
	v_mfma_f32_16x16x32_bf16 v[86:89], v[192:195], v[212:215], v[86:89]
	v_mfma_f32_16x16x32_bf16 v[82:85], v[188:191], v[216:219], v[82:85]
	v_mfma_f32_16x16x32_bf16 v[78:81], v[196:199], v[114:117], v[78:81]
	v_mfma_f32_16x16x32_bf16 v[74:77], v[196:199], v[216:219], v[74:77]
	v_mfma_f32_16x16x32_bf16 v[70:73], v[204:207], v[114:117], v[70:73]
	v_mfma_f32_16x16x32_bf16 v[66:69], v[204:207], v[216:219], v[66:69]
	v_mfma_f32_16x16x32_bf16 v[224:227], v[184:187], v[212:215], v[94:97]
	v_mfma_f32_16x16x32_bf16 v[164:167], v[192:195], v[220:223], v[82:85]
	v_mfma_f32_16x16x32_bf16 v[184:187], v[200:203], v[212:215], v[78:81]
	v_mfma_f32_16x16x32_bf16 v[188:191], v[200:203], v[220:223], v[74:77]
	v_mfma_f32_16x16x32_bf16 v[192:195], v[208:211], v[212:215], v[70:73]
	v_mfma_f32_16x16x32_bf16 v[196:199], v[208:211], v[220:223], v[66:69]
	s_setprio 0
	s_barrier
	s_nop 0
	ds_read_b128 v[66:69], v133 offset:16384
	ds_read_b128 v[70:73], v133 offset:17408
	ds_read_b128 v[74:77], v134 offset:16384
	ds_read_b128 v[78:81], v134 offset:17408
	ds_read_b128 v[82:85], v137 offset:16384
	ds_read_b128 v[94:97], v137 offset:17408
	ds_read_b128 v[200:203], v139 offset:16384
	ds_read_b128 v[204:207], v139 offset:17408
	s_waitcnt vmcnt(4)
	s_barrier
	s_waitcnt lgkmcnt(0)
	s_setprio 1
	s_waitcnt lgkmcnt(0)
	v_mfma_f32_16x16x32_bf16 v[62:65], v[66:69], v[148:151], v[62:65]
	v_mfma_f32_16x16x32_bf16 v[58:61], v[66:69], v[156:159], v[58:61]
	v_mfma_f32_16x16x32_bf16 v[54:57], v[74:77], v[148:151], v[54:57]
	v_mfma_f32_16x16x32_bf16 v[50:53], v[74:77], v[156:159], v[50:53]
	v_mfma_f32_16x16x32_bf16 v[46:49], v[82:85], v[148:151], v[46:49]
	v_mfma_f32_16x16x32_bf16 v[42:45], v[82:85], v[156:159], v[42:45]
	v_mfma_f32_16x16x32_bf16 v[38:41], v[200:203], v[148:151], v[38:41]
	v_mfma_f32_16x16x32_bf16 v[34:37], v[200:203], v[156:159], v[34:37]
	v_mfma_f32_16x16x32_bf16 v[62:65], v[70:73], v[152:155], v[62:65]
	v_mfma_f32_16x16x32_bf16 v[58:61], v[70:73], v[160:163], v[58:61]
	v_mfma_f32_16x16x32_bf16 v[54:57], v[78:81], v[152:155], v[54:57]
	v_mfma_f32_16x16x32_bf16 v[50:53], v[78:81], v[160:163], v[50:53]
	v_mfma_f32_16x16x32_bf16 v[46:49], v[94:97], v[152:155], v[46:49]
	v_mfma_f32_16x16x32_bf16 v[42:45], v[94:97], v[160:163], v[42:45]
	v_mfma_f32_16x16x32_bf16 v[38:41], v[204:207], v[152:155], v[38:41]
	v_mfma_f32_16x16x32_bf16 v[34:37], v[204:207], v[160:163], v[34:37]
	s_setprio 0
	s_setprio 1
	v_mfma_f32_16x16x32_bf16 v[30:33], v[66:69], v[114:117], v[30:33]
	v_mfma_f32_16x16x32_bf16 v[26:29], v[66:69], v[216:219], v[26:29]
	v_mfma_f32_16x16x32_bf16 v[22:25], v[74:77], v[114:117], v[22:25]
	v_mfma_f32_16x16x32_bf16 v[18:21], v[74:77], v[216:219], v[18:21]
	v_mfma_f32_16x16x32_bf16 v[14:17], v[82:85], v[114:117], v[14:17]
	v_mfma_f32_16x16x32_bf16 v[10:13], v[82:85], v[216:219], v[10:13]
	v_mfma_f32_16x16x32_bf16 v[6:9], v[200:203], v[114:117], v[6:9]
	v_mfma_f32_16x16x32_bf16 v[2:5], v[200:203], v[216:219], v[2:5]
	v_mfma_f32_16x16x32_bf16 v[148:151], v[70:73], v[212:215], v[30:33]
	v_mfma_f32_16x16x32_bf16 v[152:155], v[70:73], v[220:223], v[26:29]
	v_mfma_f32_16x16x32_bf16 v[156:159], v[78:81], v[212:215], v[22:25]
	v_mfma_f32_16x16x32_bf16 v[160:163], v[78:81], v[220:223], v[18:21]
	v_mfma_f32_16x16x32_bf16 v[208:211], v[94:97], v[212:215], v[14:17]
	v_mfma_f32_16x16x32_bf16 v[228:231], v[94:97], v[220:223], v[10:13]
	v_mfma_f32_16x16x32_bf16 v[212:215], v[204:207], v[212:215], v[6:9]
	v_mfma_f32_16x16x32_bf16 v[200:203], v[204:207], v[220:223], v[2:5]
	s_setprio 0
	s_barrier
	ds_read_b128 v[14:17], v145
	ds_read_b128 v[30:33], v145 offset:1024
	ds_read_b128 v[204:207], v145 offset:2048
	ds_read_b128 v[216:219], v145 offset:3072
	ds_read_b128 v[2:5], v133 offset:32768
	ds_read_b128 v[6:9], v133 offset:33792
	ds_read_b128 v[10:13], v134 offset:32768
	ds_read_b128 v[18:21], v134 offset:33792
	ds_read_b128 v[22:25], v137 offset:32768
	ds_read_b128 v[26:29], v137 offset:33792
	ds_read_b128 v[220:223], v139 offset:32768
	ds_read_b128 v[232:235], v139 offset:33792
	s_waitcnt vmcnt(2)
	s_barrier
; #define LDA(dst, b, h) for (int m = 0; m < 4; ++m) for (int k = 0; k < 2; ++k) \
;     dst[m][k] = *reinterpret_cast<const bf16x8*>((char*)SA(b, h) + lds_byte(wr * 64 + m * 16 + fr, k * 32 + fq * 8))
; #define LDB(dst, b, h) for (int n = 0; n < 2; ++n) for (int k = 0; k < 2; ++k) \
;     dst[n][k] = *reinterpret_cast<const bf16x8*>((char*)SB(b, h) + lds_byte(wc * 32 + n * 16 + fr, k * 32 + fq * 8))
; #define MMA(ai, bj, At, Bt_) do { __builtin_amdgcn_s_setprio(1); \
;     for (int m = 0; m < 4; ++m) for (int n = 0; n < 2; ++n) for (int k = 0; k < 2; ++k) \
;       acc[ai][bj][m][n] = __builtin_amdgcn_mfma_f32_16x16x32_bf16(At[m][k], Bt_[n][k], acc[ai][bj][m][n], 0, 0, 0); \
;     __builtin_amdgcn_s_setprio(0); } while (0)
; #define WAIT_V(n) asm volatile("s_waitcnt vmcnt(" #n ")" ::: "memory")
; #define WAIT_L(n) asm volatile("s_waitcnt lgkmcnt(" #n ")" ::: "memory")
; #define BAR __builtin_amdgcn_s_barrier()
;     ...
;     { LDB(B0, 1, 0); LDA(At, 1, 0); WAIT_V(2); BAR; WAIT_L(0); MMA(0, 0, At, B0); BAR;
;       LDB(B1, 1, 1); WAIT_V(0); BAR; WAIT_L(0); MMA(0, 1, At, B1); BAR;
;       LDA(At, 1, 1); BAR; WAIT_L(0); MMA(1, 0, At, B0); MMA(1, 1, At, B1); BAR; }
;     if (wr == 0) BAR;
	s_waitcnt lgkmcnt(0)
	s_setprio 1
	s_waitcnt lgkmcnt(0)
	v_mfma_f32_16x16x32_bf16 v[66:69], v[2:5], v[14:17], v[126:129]
	v_mfma_f32_16x16x32_bf16 v[114:117], v[6:9], v[30:33], v[66:69]
	v_mfma_f32_16x16x32_bf16 v[66:69], v[2:5], v[204:207], v[122:125]
	v_mfma_f32_16x16x32_bf16 v[126:129], v[6:9], v[216:219], v[66:69]
	v_mfma_f32_16x16x32_bf16 v[66:69], v[10:13], v[14:17], v[118:121]
	v_mfma_f32_16x16x32_bf16 v[82:85], v[18:21], v[30:33], v[66:69]
	v_mfma_f32_16x16x32_bf16 v[66:69], v[10:13], v[204:207], v[140:143]
	v_mfma_f32_16x16x32_bf16 v[94:97], v[18:21], v[216:219], v[66:69]
	v_mfma_f32_16x16x32_bf16 v[66:69], v[22:25], v[14:17], v[110:113]
	v_mfma_f32_16x16x32_bf16 v[74:77], v[26:29], v[30:33], v[66:69]
	v_mfma_f32_16x16x32_bf16 v[66:69], v[22:25], v[204:207], v[106:109]
	v_mfma_f32_16x16x32_bf16 v[78:81], v[26:29], v[216:219], v[66:69]
	v_mfma_f32_16x16x32_bf16 v[66:69], v[220:223], v[14:17], v[102:105]
	v_mfma_f32_16x16x32_bf16 v[70:73], v[220:223], v[204:207], v[98:101]
	v_mfma_f32_16x16x32_bf16 v[66:69], v[232:235], v[30:33], v[66:69]
	v_mfma_f32_16x16x32_bf16 v[70:73], v[232:235], v[216:219], v[70:73]
	s_setprio 0
	s_barrier
	ds_read_b128 v[140:143], v146
	ds_read_b128 v[236:239], v146 offset:1024
	ds_read_b128 v[240:243], v146 offset:2048
	ds_read_b128 v[144:147], v146 offset:3072
	s_waitcnt vmcnt(0)
	s_barrier
	s_waitcnt lgkmcnt(0)
	s_setprio 1
	s_waitcnt lgkmcnt(0)
	v_mfma_f32_16x16x32_bf16 v[98:101], v[2:5], v[140:143], v[224:227]
	v_mfma_f32_16x16x32_bf16 v[2:5], v[2:5], v[240:243], v[90:93]
	v_mfma_f32_16x16x32_bf16 v[118:121], v[6:9], v[144:147], v[2:5]
	v_mfma_f32_16x16x32_bf16 v[2:5], v[10:13], v[140:143], v[86:89]
	v_mfma_f32_16x16x32_bf16 v[102:105], v[18:21], v[236:239], v[2:5]
	v_mfma_f32_16x16x32_bf16 v[2:5], v[10:13], v[240:243], v[164:167]
	v_mfma_f32_16x16x32_bf16 v[122:125], v[18:21], v[144:147], v[2:5]
	v_mfma_f32_16x16x32_bf16 v[2:5], v[22:25], v[140:143], v[184:187]
	v_mfma_f32_16x16x32_bf16 v[90:93], v[26:29], v[236:239], v[2:5]
	v_mfma_f32_16x16x32_bf16 v[2:5], v[22:25], v[240:243], v[188:191]
	v_mfma_f32_16x16x32_bf16 v[110:113], v[26:29], v[144:147], v[2:5]
	v_mfma_f32_16x16x32_bf16 v[2:5], v[220:223], v[140:143], v[192:195]
	v_mfma_f32_16x16x32_bf16 v[86:89], v[232:235], v[236:239], v[2:5]
	v_mfma_f32_16x16x32_bf16 v[2:5], v[220:223], v[240:243], v[196:199]
	v_mfma_f32_16x16x32_bf16 v[98:101], v[6:9], v[236:239], v[98:101]
	v_mfma_f32_16x16x32_bf16 v[106:109], v[232:235], v[144:147], v[2:5]
	s_setprio 0
	s_barrier
	ds_read_b128 v[164:167], v133 offset:49152
	ds_read_b128 v[184:187], v133 offset:50176
	ds_read_b128 v[188:191], v134 offset:49152
	ds_read_b128 v[192:195], v134 offset:50176
	ds_read_b128 v[196:199], v137 offset:49152
	ds_read_b128 v[220:223], v137 offset:50176
	ds_read_b128 v[224:227], v139 offset:49152
	ds_read_b128 v[232:235], v139 offset:50176
	s_barrier
	s_waitcnt lgkmcnt(0)
	s_setprio 1
	s_waitcnt lgkmcnt(0)
	v_mfma_f32_16x16x32_bf16 v[6:9], v[164:167], v[204:207], v[58:61]
	v_mfma_f32_16x16x32_bf16 v[10:13], v[188:191], v[204:207], v[50:53]
	v_mfma_f32_16x16x32_bf16 v[2:5], v[164:167], v[14:17], v[62:65]
	v_mfma_f32_16x16x32_bf16 v[18:21], v[184:187], v[216:219], v[6:9]
	v_mfma_f32_16x16x32_bf16 v[6:9], v[188:191], v[14:17], v[54:57]
	v_mfma_f32_16x16x32_bf16 v[22:25], v[192:195], v[216:219], v[10:13]
	v_mfma_f32_16x16x32_bf16 v[10:13], v[196:199], v[14:17], v[46:49]
	v_mfma_f32_16x16x32_bf16 v[14:17], v[224:227], v[14:17], v[38:41]
	v_mfma_f32_16x16x32_bf16 v[2:5], v[184:187], v[30:33], v[2:5]
	v_mfma_f32_16x16x32_bf16 v[6:9], v[192:195], v[30:33], v[6:9]
	v_mfma_f32_16x16x32_bf16 v[10:13], v[220:223], v[30:33], v[10:13]
	v_mfma_f32_16x16x32_bf16 v[26:29], v[196:199], v[204:207], v[42:45]
	v_mfma_f32_16x16x32_bf16 v[14:17], v[232:235], v[30:33], v[14:17]
	v_mfma_f32_16x16x32_bf16 v[30:33], v[224:227], v[204:207], v[34:37]
	v_mfma_f32_16x16x32_bf16 v[26:29], v[220:223], v[216:219], v[26:29]
	v_mfma_f32_16x16x32_bf16 v[30:33], v[232:235], v[216:219], v[30:33]
	s_setprio 0
	s_setprio 1
	v_mfma_f32_16x16x32_bf16 v[38:41], v[164:167], v[240:243], v[152:155]
	v_mfma_f32_16x16x32_bf16 v[42:45], v[188:191], v[240:243], v[160:163]
	v_mfma_f32_16x16x32_bf16 v[46:49], v[196:199], v[240:243], v[228:231]
	v_mfma_f32_16x16x32_bf16 v[34:37], v[164:167], v[140:143], v[148:151]
	v_mfma_f32_16x16x32_bf16 v[50:53], v[184:187], v[144:147], v[38:41]
	v_mfma_f32_16x16x32_bf16 v[38:41], v[188:191], v[140:143], v[156:159]
	v_mfma_f32_16x16x32_bf16 v[54:57], v[192:195], v[144:147], v[42:45]
	v_mfma_f32_16x16x32_bf16 v[42:45], v[196:199], v[140:143], v[208:211]
	v_mfma_f32_16x16x32_bf16 v[58:61], v[220:223], v[144:147], v[46:49]
	v_mfma_f32_16x16x32_bf16 v[46:49], v[224:227], v[140:143], v[212:215]
	v_mfma_f32_16x16x32_bf16 v[62:65], v[224:227], v[240:243], v[200:203]
	v_mfma_f32_16x16x32_bf16 v[34:37], v[184:187], v[236:239], v[34:37]
	v_mfma_f32_16x16x32_bf16 v[38:41], v[192:195], v[236:239], v[38:41]
	v_mfma_f32_16x16x32_bf16 v[42:45], v[220:223], v[236:239], v[42:45]
	v_mfma_f32_16x16x32_bf16 v[46:49], v[232:235], v[236:239], v[46:49]
	v_mfma_f32_16x16x32_bf16 v[62:65], v[232:235], v[144:147], v[62:65]
	s_setprio 0
	v_readlane_b32 s4, v245, 33
	v_readlane_b32 s5, v245, 34
	s_and_b64 vcc, exec, s[4:5]
	s_barrier
	s_cbranch_vccz .LBB0_101
	s_barrier

; #define LDA(dst, b, h) for (int m = 0; m < 4; ++m) for (int k = 0; k < 2; ++k) \
;     dst[m][k] = *reinterpret_cast<const bf16x8*>((char*)SA(b, h) + lds_byte(wr * 64 + m * 16 + fr, k * 32 + fq * 8))
; #define LDB(dst, b, h) for (int n = 0; n < 2; ++n) for (int k = 0; k < 2; ++k) \
;     dst[n][k] = *reinterpret_cast<const bf16x8*>((char*)SB(b, h) + lds_byte(wc * 32 + n * 16 + fr, k * 32 + fq * 8))
; #define MMA(ai, bj, At, Bt_) do { __builtin_amdgcn_s_setprio(1); \
;     for (int m = 0; m < 4; ++m) for (int n = 0; n < 2; ++n) for (int k = 0; k < 2; ++k) \
;       acc[ai][bj][m][n] = __builtin_amdgcn_mfma_f32_16x16x32_bf16(At[m][k], Bt_[n][k], acc[ai][bj][m][n], 0, 0, 0); \
;     __builtin_amdgcn_s_setprio(0); } while (0)
; #define WAIT_L(n) asm volatile("s_waitcnt lgkmcnt(" #n ")" ::: "memory")
; #define BAR __builtin_amdgcn_s_barrier()
; #define SCHED __builtin_amdgcn_sched_barrier(0)
;     ...
;       LDB(B0, 0, 0); SCHED; LDA(At, 0, 0); STAGE(SA(1, 1), A, brow + HALF, t + 1);
;       WAIT_L(8); BAR; WAIT_L(0); MMA(0, 0, At, B0); BAR; SCHED;
;       LDB(B1, 0, 1); STAGE(SB(0, 0), Bt, bcol, t + 2);
;       BAR; WAIT_L(0); MMA(0, 1, At, B1); BAR;
;       LDA(At, 0, 1); STAGE(SA(0, 0), A, brow, t + 2);
;       BAR; WAIT_L(0); MMA(1, 0, At, B0); BAR; SCHED;
.LBB0_155:
	v_add_u32_e32 v143, s2, v142
	ds_read_b128 v[146:149], v143
	ds_read_b128 v[150:153], v143 offset:1024
	ds_read_b128 v[154:157], v143 offset:2048
	ds_read_b128 v[158:161], v143 offset:3072
	s_add_u32 s40, s30, s10
	s_addc_u32 s41, s31, s11
	s_add_u32 s42, s40, 0x80080
	s_addc_u32 s43, s41, 0
	s_add_i32 s39, s24, 0xc000
	ds_read_b128 v[162:165], v133
	ds_read_b128 v[184:187], v133 offset:1024
	ds_read_b128 v[188:191], v134
	ds_read_b128 v[192:195], v134 offset:1024
	ds_read_b128 v[196:199], v137
	ds_read_b128 v[200:203], v137 offset:1024
	ds_read_b128 v[204:207], v139
	ds_read_b128 v[208:211], v139 offset:1024
	s_mov_b32 m0, s39
	v_lshl_add_u64 v[144:145], s[42:43], 0, v[0:1]
	s_add_i32 s38, s24, 0xe000
	global_load_lds_dwordx4 v[144:145], off
	v_lshl_add_u64 v[144:145], s[42:43], 0, v[140:141]
	s_mov_b32 m0, s38
	s_nop 0
	global_load_lds_dwordx4 v[144:145], off
	s_waitcnt lgkmcnt(8)
	s_barrier
	s_waitcnt lgkmcnt(0)
	s_setprio 0
	s_waitcnt lgkmcnt(0)
	v_mfma_f32_16x16x32_bf16 v[126:129], v[162:165], v[146:149], v[126:129]
	v_mfma_f32_16x16x32_bf16 v[122:125], v[162:165], v[154:157], v[122:125]
	v_mfma_f32_16x16x32_bf16 v[118:121], v[188:191], v[146:149], v[118:121]
	v_mfma_f32_16x16x32_bf16 v[114:117], v[188:191], v[154:157], v[114:117]
	v_mfma_f32_16x16x32_bf16 v[110:113], v[196:199], v[146:149], v[110:113]
	v_mfma_f32_16x16x32_bf16 v[106:109], v[196:199], v[154:157], v[106:109]
	v_mfma_f32_16x16x32_bf16 v[102:105], v[204:207], v[146:149], v[102:105]
	v_mfma_f32_16x16x32_bf16 v[98:101], v[204:207], v[154:157], v[98:101]
	v_mfma_f32_16x16x32_bf16 v[126:129], v[184:187], v[150:153], v[126:129]
	v_mfma_f32_16x16x32_bf16 v[122:125], v[184:187], v[158:161], v[122:125]
	v_mfma_f32_16x16x32_bf16 v[118:121], v[192:195], v[150:153], v[118:121]
	v_mfma_f32_16x16x32_bf16 v[114:117], v[192:195], v[158:161], v[114:117]
	v_mfma_f32_16x16x32_bf16 v[110:113], v[200:203], v[150:153], v[110:113]
	v_mfma_f32_16x16x32_bf16 v[106:109], v[200:203], v[158:161], v[106:109]
	v_mfma_f32_16x16x32_bf16 v[102:105], v[208:211], v[150:153], v[102:105]
	v_mfma_f32_16x16x32_bf16 v[98:101], v[208:211], v[158:161], v[98:101]
	s_setprio 1
	s_barrier
	s_add_u32 s42, s34, s10
	s_addc_u32 s43, s35, s11
	s_add_u32 s44, s42, 0x100
	v_add_u32_e32 v144, s76, v142
	s_addc_u32 s45, s43, 0
	s_mov_b32 m0, s25
	ds_read_b128 v[212:215], v144
	ds_read_b128 v[216:219], v144 offset:1024
	ds_read_b128 v[220:223], v144 offset:2048
	ds_read_b128 v[224:227], v144 offset:3072
	s_nop 0
	v_lshl_add_u64 v[166:167], s[44:45], 0, v[0:1]
	global_load_lds_dwordx4 v[166:167], off
	v_lshl_add_u64 v[166:167], s[44:45], 0, v[140:141]
	s_mov_b32 m0, s26
	s_nop 0
	global_load_lds_dwordx4 v[166:167], off
	s_barrier
	s_waitcnt lgkmcnt(0)
	s_setprio 0
	s_waitcnt lgkmcnt(0)
	v_mfma_f32_16x16x32_bf16 v[94:97], v[162:165], v[212:215], v[94:97]
	v_mfma_f32_16x16x32_bf16 v[90:93], v[162:165], v[220:223], v[90:93]
	v_mfma_f32_16x16x32_bf16 v[86:89], v[188:191], v[212:215], v[86:89]
	v_mfma_f32_16x16x32_bf16 v[82:85], v[188:191], v[220:223], v[82:85]
	v_mfma_f32_16x16x32_bf16 v[78:81], v[196:199], v[212:215], v[78:81]
	v_mfma_f32_16x16x32_bf16 v[74:77], v[196:199], v[220:223], v[74:77]
	v_mfma_f32_16x16x32_bf16 v[70:73], v[204:207], v[212:215], v[70:73]
	v_mfma_f32_16x16x32_bf16 v[66:69], v[204:207], v[220:223], v[66:69]
	v_mfma_f32_16x16x32_bf16 v[94:97], v[184:187], v[216:219], v[94:97]
	v_mfma_f32_16x16x32_bf16 v[90:93], v[184:187], v[224:227], v[90:93]
	v_mfma_f32_16x16x32_bf16 v[86:89], v[192:195], v[216:219], v[86:89]
	v_mfma_f32_16x16x32_bf16 v[82:85], v[192:195], v[224:227], v[82:85]
	v_mfma_f32_16x16x32_bf16 v[78:81], v[200:203], v[216:219], v[78:81]
	v_mfma_f32_16x16x32_bf16 v[74:77], v[200:203], v[224:227], v[74:77]
	v_mfma_f32_16x16x32_bf16 v[70:73], v[208:211], v[216:219], v[70:73]
	v_mfma_f32_16x16x32_bf16 v[66:69], v[208:211], v[224:227], v[66:69]
	s_setprio 1
	s_add_u32 s44, s40, 0x100
	s_addc_u32 s45, s41, 0
	s_mov_b32 m0, s24
	s_barrier
	ds_read_b128 v[162:165], v133 offset:16384
	ds_read_b128 v[184:187], v133 offset:17408
	ds_read_b128 v[188:191], v134 offset:16384
	ds_read_b128 v[192:195], v134 offset:17408
	ds_read_b128 v[196:199], v137 offset:16384
	ds_read_b128 v[200:203], v137 offset:17408
	ds_read_b128 v[204:207], v139 offset:16384
	ds_read_b128 v[208:211], v139 offset:17408
	s_nop 0
	v_lshl_add_u64 v[166:167], s[44:45], 0, v[0:1]
	global_load_lds_dwordx4 v[166:167], off
	v_lshl_add_u64 v[166:167], s[44:45], 0, v[140:141]
	s_mov_b32 m0, s9
	s_nop 0
	global_load_lds_dwordx4 v[166:167], off
	s_barrier
	s_waitcnt lgkmcnt(0)
	s_setprio 0
	s_waitcnt lgkmcnt(0)
	v_mfma_f32_16x16x32_bf16 v[62:65], v[162:165], v[146:149], v[62:65]
	v_mfma_f32_16x16x32_bf16 v[58:61], v[162:165], v[154:157], v[58:61]
	v_mfma_f32_16x16x32_bf16 v[54:57], v[188:191], v[146:149], v[54:57]
	v_mfma_f32_16x16x32_bf16 v[50:53], v[188:191], v[154:157], v[50:53]
	v_mfma_f32_16x16x32_bf16 v[46:49], v[196:199], v[146:149], v[46:49]
	v_mfma_f32_16x16x32_bf16 v[42:45], v[196:199], v[154:157], v[42:45]
	v_mfma_f32_16x16x32_bf16 v[38:41], v[204:207], v[146:149], v[38:41]
	v_mfma_f32_16x16x32_bf16 v[34:37], v[204:207], v[154:157], v[34:37]
	v_mfma_f32_16x16x32_bf16 v[62:65], v[184:187], v[150:153], v[62:65]
	v_mfma_f32_16x16x32_bf16 v[58:61], v[184:187], v[158:161], v[58:61]
	v_mfma_f32_16x16x32_bf16 v[54:57], v[192:195], v[150:153], v[54:57]
	v_mfma_f32_16x16x32_bf16 v[50:53], v[192:195], v[158:161], v[50:53]
	v_mfma_f32_16x16x32_bf16 v[46:49], v[200:203], v[150:153], v[46:49]
	v_mfma_f32_16x16x32_bf16 v[42:45], v[200:203], v[158:161], v[42:45]
	v_mfma_f32_16x16x32_bf16 v[38:41], v[208:211], v[150:153], v[38:41]
	v_mfma_f32_16x16x32_bf16 v[34:37], v[208:211], v[158:161], v[34:37]
	s_setprio 1
	s_barrier
; #define LDA(dst, b, h) for (int m = 0; m < 4; ++m) for (int k = 0; k < 2; ++k) \
;     dst[m][k] = *reinterpret_cast<const bf16x8*>((char*)SA(b, h) + lds_byte(wr * 64 + m * 16 + fr, k * 32 + fq * 8))
; #define LDB(dst, b, h) for (int n = 0; n < 2; ++n) for (int k = 0; k < 2; ++k) \
;     dst[n][k] = *reinterpret_cast<const bf16x8*>((char*)SB(b, h) + lds_byte(wc * 32 + n * 16 + fr, k * 32 + fq * 8))
; #define MMA(ai, bj, At, Bt_) do { __builtin_amdgcn_s_setprio(1); \
;     for (int m = 0; m < 4; ++m) for (int n = 0; n < 2; ++n) for (int k = 0; k < 2; ++k) \
;       acc[ai][bj][m][n] = __builtin_amdgcn_mfma_f32_16x16x32_bf16(At[m][k], Bt_[n][k], acc[ai][bj][m][n], 0, 0, 0); \
;     __builtin_amdgcn_s_setprio(0); } while (0)
; #define WAIT_V(n) asm volatile("s_waitcnt vmcnt(" #n ")" ::: "memory")
; #define WAIT_L(n) asm volatile("s_waitcnt lgkmcnt(" #n ")" ::: "memory")
; #define BAR __builtin_amdgcn_s_barrier()
; #define SCHED __builtin_amdgcn_sched_barrier(0)
;     ...
;       STAGE(SB(0, 1), Bt, bcol + HALF, t + 2);
;       WAIT_V(6); BAR; MMA(1, 1, At, B1); BAR;
;       LDB(B0, 1, 0); SCHED; LDA(At, 1, 0); STAGE(SA(0, 1), A, brow + HALF, t + 2);
;       WAIT_L(8); BAR; WAIT_L(0); MMA(0, 0, At, B0); BAR; SCHED;
;       LDB(B1, 1, 1); STAGE(SB(1, 0), Bt, bcol, t + 3);
;       BAR; WAIT_L(0); MMA(0, 1, At, B1); BAR;
;       LDA(At, 1, 1); STAGE(SA(1, 0), A, brow, t + 3);
	s_add_u32 s44, s42, 0x80100
	s_addc_u32 s45, s43, 0
	s_mov_b32 m0, s27
	s_nop 0
	v_lshl_add_u64 v[146:147], s[44:45], 0, v[0:1]
	global_load_lds_dwordx4 v[146:147], off
	v_lshl_add_u64 v[146:147], s[44:45], 0, v[140:141]
	s_mov_b32 m0, s28
	s_nop 0
	global_load_lds_dwordx4 v[146:147], off
	s_waitcnt vmcnt(6)
	s_barrier
	s_setprio 0
	v_mfma_f32_16x16x32_bf16 v[30:33], v[162:165], v[212:215], v[30:33]
	v_mfma_f32_16x16x32_bf16 v[26:29], v[162:165], v[220:223], v[26:29]
	v_mfma_f32_16x16x32_bf16 v[22:25], v[188:191], v[212:215], v[22:25]
	v_mfma_f32_16x16x32_bf16 v[18:21], v[188:191], v[220:223], v[18:21]
	v_mfma_f32_16x16x32_bf16 v[14:17], v[196:199], v[212:215], v[14:17]
	v_mfma_f32_16x16x32_bf16 v[10:13], v[196:199], v[220:223], v[10:13]
	v_mfma_f32_16x16x32_bf16 v[6:9], v[204:207], v[212:215], v[6:9]
	v_mfma_f32_16x16x32_bf16 v[2:5], v[204:207], v[220:223], v[2:5]
	v_mfma_f32_16x16x32_bf16 v[30:33], v[184:187], v[216:219], v[30:33]
	v_mfma_f32_16x16x32_bf16 v[26:29], v[184:187], v[224:227], v[26:29]
	v_mfma_f32_16x16x32_bf16 v[22:25], v[192:195], v[216:219], v[22:25]
	v_mfma_f32_16x16x32_bf16 v[18:21], v[192:195], v[224:227], v[18:21]
	v_mfma_f32_16x16x32_bf16 v[14:17], v[200:203], v[216:219], v[14:17]
	v_mfma_f32_16x16x32_bf16 v[10:13], v[200:203], v[224:227], v[10:13]
	v_mfma_f32_16x16x32_bf16 v[6:9], v[208:211], v[216:219], v[6:9]
	v_mfma_f32_16x16x32_bf16 v[2:5], v[208:211], v[224:227], v[2:5]
	s_setprio 1
	v_add_u32_e32 v145, s77, v142
	s_barrier
	ds_read_b128 v[148:151], v145
	ds_read_b128 v[152:155], v145 offset:1024
	ds_read_b128 v[156:159], v145 offset:2048
	ds_read_b128 v[160:163], v145 offset:3072
	s_add_u32 s44, s40, 0x80100
	s_addc_u32 s45, s41, 0
	s_mov_b32 m0, s7
	ds_read_b128 v[164:167], v133 offset:32768
	ds_read_b128 v[184:187], v133 offset:33792
	ds_read_b128 v[188:191], v134 offset:32768
	ds_read_b128 v[192:195], v134 offset:33792
	ds_read_b128 v[196:199], v137 offset:32768
	ds_read_b128 v[200:203], v137 offset:33792
	ds_read_b128 v[204:207], v139 offset:32768
	ds_read_b128 v[208:211], v139 offset:33792
	s_nop 0
	v_lshl_add_u64 v[146:147], s[44:45], 0, v[0:1]
	global_load_lds_dwordx4 v[146:147], off
	v_lshl_add_u64 v[146:147], s[44:45], 0, v[140:141]
	s_mov_b32 m0, s29
	s_nop 0
	global_load_lds_dwordx4 v[146:147], off
	s_waitcnt lgkmcnt(8)
	s_barrier
	s_waitcnt lgkmcnt(0)
	s_setprio 0
	s_waitcnt lgkmcnt(0)
	v_mfma_f32_16x16x32_bf16 v[126:129], v[164:167], v[148:151], v[126:129]
	v_mfma_f32_16x16x32_bf16 v[122:125], v[164:167], v[156:159], v[122:125]
	v_mfma_f32_16x16x32_bf16 v[118:121], v[188:191], v[148:151], v[118:121]
	v_mfma_f32_16x16x32_bf16 v[114:117], v[188:191], v[156:159], v[114:117]
	v_mfma_f32_16x16x32_bf16 v[110:113], v[196:199], v[148:151], v[110:113]
	v_mfma_f32_16x16x32_bf16 v[106:109], v[196:199], v[156:159], v[106:109]
	v_mfma_f32_16x16x32_bf16 v[102:105], v[204:207], v[148:151], v[102:105]
	v_mfma_f32_16x16x32_bf16 v[98:101], v[204:207], v[156:159], v[98:101]
	v_mfma_f32_16x16x32_bf16 v[126:129], v[184:187], v[152:155], v[126:129]
	v_mfma_f32_16x16x32_bf16 v[122:125], v[184:187], v[160:163], v[122:125]
	v_mfma_f32_16x16x32_bf16 v[118:121], v[192:195], v[152:155], v[118:121]
	v_mfma_f32_16x16x32_bf16 v[114:117], v[192:195], v[160:163], v[114:117]
	v_mfma_f32_16x16x32_bf16 v[110:113], v[200:203], v[152:155], v[110:113]
	v_mfma_f32_16x16x32_bf16 v[106:109], v[200:203], v[160:163], v[106:109]
	v_mfma_f32_16x16x32_bf16 v[102:105], v[208:211], v[152:155], v[102:105]
	v_mfma_f32_16x16x32_bf16 v[98:101], v[208:211], v[160:163], v[98:101]
	s_setprio 1
	s_barrier
	s_add_u32 s44, s42, 0x180
	v_add_u32_e32 v146, s78, v142
	s_addc_u32 s45, s43, 0
	s_mov_b32 m0, s12
	ds_read_b128 v[212:215], v146
	ds_read_b128 v[216:219], v146 offset:1024
	ds_read_b128 v[220:223], v146 offset:2048
	ds_read_b128 v[224:227], v146 offset:3072
	s_nop 0
	v_lshl_add_u64 v[228:229], s[44:45], 0, v[0:1]
	global_load_lds_dwordx4 v[228:229], off
	v_lshl_add_u64 v[228:229], s[44:45], 0, v[140:141]
	s_mov_b32 m0, s13
	s_nop 0
	global_load_lds_dwordx4 v[228:229], off
	s_barrier
	s_waitcnt lgkmcnt(0)
	s_setprio 0
	s_waitcnt lgkmcnt(0)
	v_mfma_f32_16x16x32_bf16 v[94:97], v[164:167], v[212:215], v[94:97]
	v_mfma_f32_16x16x32_bf16 v[90:93], v[164:167], v[220:223], v[90:93]
	v_mfma_f32_16x16x32_bf16 v[86:89], v[188:191], v[212:215], v[86:89]
	v_mfma_f32_16x16x32_bf16 v[82:85], v[188:191], v[220:223], v[82:85]
	v_mfma_f32_16x16x32_bf16 v[78:81], v[196:199], v[212:215], v[78:81]
	v_mfma_f32_16x16x32_bf16 v[74:77], v[196:199], v[220:223], v[74:77]
	v_mfma_f32_16x16x32_bf16 v[70:73], v[204:207], v[212:215], v[70:73]
	v_mfma_f32_16x16x32_bf16 v[66:69], v[204:207], v[220:223], v[66:69]
	v_mfma_f32_16x16x32_bf16 v[94:97], v[184:187], v[216:219], v[94:97]
	v_mfma_f32_16x16x32_bf16 v[90:93], v[184:187], v[224:227], v[90:93]
	v_mfma_f32_16x16x32_bf16 v[86:89], v[192:195], v[216:219], v[86:89]
	v_mfma_f32_16x16x32_bf16 v[82:85], v[192:195], v[224:227], v[82:85]
	v_mfma_f32_16x16x32_bf16 v[78:81], v[200:203], v[216:219], v[78:81]
	v_mfma_f32_16x16x32_bf16 v[74:77], v[200:203], v[224:227], v[74:77]
	v_mfma_f32_16x16x32_bf16 v[70:73], v[208:211], v[216:219], v[70:73]
	v_mfma_f32_16x16x32_bf16 v[66:69], v[208:211], v[224:227], v[66:69]
	s_setprio 1
	s_add_u32 s40, s40, 0x180
	s_addc_u32 s41, s41, 0
	s_mov_b32 m0, s14
	s_barrier
	ds_read_b128 v[164:167], v133 offset:49152
	ds_read_b128 v[184:187], v133 offset:50176
	ds_read_b128 v[188:191], v134 offset:49152
	ds_read_b128 v[192:195], v134 offset:50176
	ds_read_b128 v[196:199], v137 offset:49152
	ds_read_b128 v[200:203], v137 offset:50176
	ds_read_b128 v[204:207], v139 offset:49152
	ds_read_b128 v[208:211], v139 offset:50176
	s_nop 0
	v_lshl_add_u64 v[228:229], s[40:41], 0, v[0:1]
	global_load_lds_dwordx4 v[228:229], off
	v_lshl_add_u64 v[228:229], s[40:41], 0, v[140:141]
	s_mov_b32 m0, s15
	s_nop 0
	global_load_lds_dwordx4 v[228:229], off
	s_barrier
; #define LDA(dst, b, h) for (int m = 0; m < 4; ++m) for (int k = 0; k < 2; ++k) \
;     dst[m][k] = *reinterpret_cast<const bf16x8*>((char*)SA(b, h) + lds_byte(wr * 64 + m * 16 + fr, k * 32 + fq * 8))
; #define LDB(dst, b, h) for (int n = 0; n < 2; ++n) for (int k = 0; k < 2; ++k) \
;     dst[n][k] = *reinterpret_cast<const bf16x8*>((char*)SB(b, h) + lds_byte(wc * 32 + n * 16 + fr, k * 32 + fq * 8))
; #define MMA(ai, bj, At, Bt_) do { __builtin_amdgcn_s_setprio(1); \
;     for (int m = 0; m < 4; ++m) for (int n = 0; n < 2; ++n) for (int k = 0; k < 2; ++k) \
;       acc[ai][bj][m][n] = __builtin_amdgcn_mfma_f32_16x16x32_bf16(At[m][k], Bt_[n][k], acc[ai][bj][m][n], 0, 0, 0); \
;     __builtin_amdgcn_s_setprio(0); } while (0)
; #define WAIT_V(n) asm volatile("s_waitcnt vmcnt(" #n ")" ::: "memory")
; #define WAIT_L(n) asm volatile("s_waitcnt lgkmcnt(" #n ")" ::: "memory")
; #define BAR __builtin_amdgcn_s_barrier()
; #define SCHED __builtin_amdgcn_sched_barrier(0)
;     ...
;       BAR; WAIT_L(0); MMA(1, 0, At, B0); BAR; SCHED;
;       STAGE(SB(1, 1), Bt, bcol + HALF, t + 3);
;       WAIT_V(6); BAR; MMA(1, 1, At, B1); BAR;
;     }
;     { LDB(B0, 0, 0); LDA(At, 0, 0); STAGE(SA(1, 1), A, brow + HALF, nt - 1);
;       BAR; WAIT_L(0); MMA(0, 0, At, B0); BAR;
;       LDB(B1, 0, 1); BAR; WAIT_L(0); MMA(0, 1, At, B1); BAR;
	s_waitcnt lgkmcnt(0)
	s_setprio 0
	s_waitcnt lgkmcnt(0)
	v_mfma_f32_16x16x32_bf16 v[62:65], v[164:167], v[148:151], v[62:65]
	v_mfma_f32_16x16x32_bf16 v[58:61], v[164:167], v[156:159], v[58:61]
	v_mfma_f32_16x16x32_bf16 v[54:57], v[188:191], v[148:151], v[54:57]
	v_mfma_f32_16x16x32_bf16 v[50:53], v[188:191], v[156:159], v[50:53]
	v_mfma_f32_16x16x32_bf16 v[46:49], v[196:199], v[148:151], v[46:49]
	v_mfma_f32_16x16x32_bf16 v[42:45], v[196:199], v[156:159], v[42:45]
	v_mfma_f32_16x16x32_bf16 v[38:41], v[204:207], v[148:151], v[38:41]
	v_mfma_f32_16x16x32_bf16 v[34:37], v[204:207], v[156:159], v[34:37]
	v_mfma_f32_16x16x32_bf16 v[62:65], v[184:187], v[152:155], v[62:65]
	v_mfma_f32_16x16x32_bf16 v[58:61], v[184:187], v[160:163], v[58:61]
	v_mfma_f32_16x16x32_bf16 v[54:57], v[192:195], v[152:155], v[54:57]
	v_mfma_f32_16x16x32_bf16 v[50:53], v[192:195], v[160:163], v[50:53]
	v_mfma_f32_16x16x32_bf16 v[46:49], v[200:203], v[152:155], v[46:49]
	v_mfma_f32_16x16x32_bf16 v[42:45], v[200:203], v[160:163], v[42:45]
	v_mfma_f32_16x16x32_bf16 v[38:41], v[208:211], v[152:155], v[38:41]
	v_mfma_f32_16x16x32_bf16 v[34:37], v[208:211], v[160:163], v[34:37]
	s_setprio 1
	s_barrier
	s_add_u32 s40, s42, 0x80180
	s_addc_u32 s41, s43, 0
	s_mov_b32 m0, s16
	s_nop 0
	v_lshl_add_u64 v[148:149], s[40:41], 0, v[0:1]
	global_load_lds_dwordx4 v[148:149], off
	v_lshl_add_u64 v[148:149], s[40:41], 0, v[140:141]
	s_mov_b32 m0, s17
	s_nop 0
	global_load_lds_dwordx4 v[148:149], off
	s_waitcnt vmcnt(6)
	s_barrier
	s_setprio 0
	v_mfma_f32_16x16x32_bf16 v[30:33], v[164:167], v[212:215], v[30:33]
	v_mfma_f32_16x16x32_bf16 v[26:29], v[164:167], v[220:223], v[26:29]
	v_mfma_f32_16x16x32_bf16 v[22:25], v[188:191], v[212:215], v[22:25]
	v_mfma_f32_16x16x32_bf16 v[18:21], v[188:191], v[220:223], v[18:21]
	v_mfma_f32_16x16x32_bf16 v[14:17], v[196:199], v[212:215], v[14:17]
	v_mfma_f32_16x16x32_bf16 v[10:13], v[196:199], v[220:223], v[10:13]
	v_mfma_f32_16x16x32_bf16 v[6:9], v[204:207], v[212:215], v[6:9]
	v_mfma_f32_16x16x32_bf16 v[2:5], v[204:207], v[220:223], v[2:5]
	v_mfma_f32_16x16x32_bf16 v[30:33], v[184:187], v[216:219], v[30:33]
	v_mfma_f32_16x16x32_bf16 v[26:29], v[184:187], v[224:227], v[26:29]
	v_mfma_f32_16x16x32_bf16 v[22:25], v[192:195], v[216:219], v[22:25]
	v_mfma_f32_16x16x32_bf16 v[18:21], v[192:195], v[224:227], v[18:21]
	v_mfma_f32_16x16x32_bf16 v[14:17], v[200:203], v[216:219], v[14:17]
	v_mfma_f32_16x16x32_bf16 v[10:13], v[200:203], v[224:227], v[10:13]
	v_mfma_f32_16x16x32_bf16 v[6:9], v[208:211], v[216:219], v[6:9]
	v_mfma_f32_16x16x32_bf16 v[2:5], v[208:211], v[224:227], v[2:5]
	s_setprio 1
	s_add_i32 s37, s37, 2
	s_add_u32 s10, s10, 0x100
	s_addc_u32 s11, s11, 0
	s_cmp_gt_u32 s37, 27
	s_barrier
	s_cbranch_scc0 .LBB0_155
	s_setprio 0
	s_add_u32 s4, s4, 0xf80
	s_addc_u32 s5, s5, 0
	s_mov_b32 m0, s39
	ds_read_b128 v[148:151], v143
	ds_read_b128 v[152:155], v143 offset:1024
	ds_read_b128 v[156:159], v143 offset:2048
	ds_read_b128 v[160:163], v143 offset:3072
	ds_read_b128 v[164:167], v133
	ds_read_b128 v[184:187], v133 offset:1024
	ds_read_b128 v[188:191], v134
	ds_read_b128 v[192:195], v134 offset:1024
	ds_read_b128 v[196:199], v137
	ds_read_b128 v[200:203], v137 offset:1024
	ds_read_b128 v[204:207], v139
	ds_read_b128 v[208:211], v139 offset:1024
	s_nop 0
	v_lshl_add_u64 v[142:143], s[4:5], 0, v[0:1]
	global_load_lds_dwordx4 v[142:143], off
	v_lshl_add_u64 v[140:141], s[4:5], 0, v[140:141]
	s_mov_b32 m0, s38
	s_nop 0
	global_load_lds_dwordx4 v[140:141], off
	s_barrier
	s_waitcnt lgkmcnt(0)
	s_setprio 1
	s_waitcnt lgkmcnt(0)
	v_mfma_f32_16x16x32_bf16 v[126:129], v[164:167], v[148:151], v[126:129]
	v_mfma_f32_16x16x32_bf16 v[118:121], v[188:191], v[148:151], v[118:121]
	v_mfma_f32_16x16x32_bf16 v[110:113], v[196:199], v[148:151], v[110:113]
	v_mfma_f32_16x16x32_bf16 v[102:105], v[204:207], v[148:151], v[102:105]
	v_mfma_f32_16x16x32_bf16 v[126:129], v[184:187], v[152:155], v[126:129]
	v_mfma_f32_16x16x32_bf16 v[122:125], v[164:167], v[156:159], v[122:125]
	v_mfma_f32_16x16x32_bf16 v[118:121], v[192:195], v[152:155], v[118:121]
	v_mfma_f32_16x16x32_bf16 v[114:117], v[188:191], v[156:159], v[114:117]
	v_mfma_f32_16x16x32_bf16 v[110:113], v[200:203], v[152:155], v[110:113]
	v_mfma_f32_16x16x32_bf16 v[106:109], v[196:199], v[156:159], v[106:109]
	v_mfma_f32_16x16x32_bf16 v[102:105], v[208:211], v[152:155], v[102:105]
	v_mfma_f32_16x16x32_bf16 v[98:101], v[204:207], v[156:159], v[98:101]
	v_mfma_f32_16x16x32_bf16 v[140:143], v[184:187], v[160:163], v[122:125]
	v_mfma_f32_16x16x32_bf16 v[212:215], v[192:195], v[160:163], v[114:117]
	v_mfma_f32_16x16x32_bf16 v[216:219], v[200:203], v[160:163], v[106:109]
	v_mfma_f32_16x16x32_bf16 v[220:223], v[208:211], v[160:163], v[98:101]
	s_setprio 0
	s_barrier
	s_nop 1
	ds_read_b128 v[98:101], v144
	ds_read_b128 v[106:109], v144 offset:1024
	ds_read_b128 v[114:117], v144 offset:2048
	ds_read_b128 v[122:125], v144 offset:3072
	s_barrier
	s_waitcnt lgkmcnt(0)
	s_setprio 1
	s_waitcnt lgkmcnt(0)
	v_mfma_f32_16x16x32_bf16 v[94:97], v[164:167], v[98:101], v[94:97]
	v_mfma_f32_16x16x32_bf16 v[86:89], v[188:191], v[98:101], v[86:89]
	v_mfma_f32_16x16x32_bf16 v[78:81], v[196:199], v[98:101], v[78:81]
	v_mfma_f32_16x16x32_bf16 v[70:73], v[204:207], v[98:101], v[70:73]
	v_mfma_f32_16x16x32_bf16 v[94:97], v[184:187], v[106:109], v[94:97]
	v_mfma_f32_16x16x32_bf16 v[90:93], v[164:167], v[114:117], v[90:93]
	v_mfma_f32_16x16x32_bf16 v[86:89], v[192:195], v[106:109], v[86:89]
	v_mfma_f32_16x16x32_bf16 v[82:85], v[188:191], v[114:117], v[82:85]
	v_mfma_f32_16x16x32_bf16 v[78:81], v[200:203], v[106:109], v[78:81]
	v_mfma_f32_16x16x32_bf16 v[74:77], v[196:199], v[114:117], v[74:77]
	v_mfma_f32_16x16x32_bf16 v[70:73], v[208:211], v[106:109], v[70:73]
	v_mfma_f32_16x16x32_bf16 v[66:69], v[204:207], v[114:117], v[66:69]
	v_mfma_f32_16x16x32_bf16 v[164:167], v[184:187], v[122:125], v[90:93]
	v_mfma_f32_16x16x32_bf16 v[184:187], v[192:195], v[122:125], v[82:85]
	v_mfma_f32_16x16x32_bf16 v[188:191], v[200:203], v[122:125], v[74:77]
	v_mfma_f32_16x16x32_bf16 v[192:195], v[208:211], v[122:125], v[66:69]
	s_setprio 0
	s_barrier
; #define LDA(dst, b, h) for (int m = 0; m < 4; ++m) for (int k = 0; k < 2; ++k) \
;     dst[m][k] = *reinterpret_cast<const bf16x8*>((char*)SA(b, h) + lds_byte(wr * 64 + m * 16 + fr, k * 32 + fq * 8))
; #define LDB(dst, b, h) for (int n = 0; n < 2; ++n) for (int k = 0; k < 2; ++k) \
;     dst[n][k] = *reinterpret_cast<const bf16x8*>((char*)SB(b, h) + lds_byte(wc * 32 + n * 16 + fr, k * 32 + fq * 8))
; #define MMA(ai, bj, At, Bt_) do { __builtin_amdgcn_s_setprio(1); \
;     for (int m = 0; m < 4; ++m) for (int n = 0; n < 2; ++n) for (int k = 0; k < 2; ++k) \
;       acc[ai][bj][m][n] = __builtin_amdgcn_mfma_f32_16x16x32_bf16(At[m][k], Bt_[n][k], acc[ai][bj][m][n], 0, 0, 0); \
;     __builtin_amdgcn_s_setprio(0); } while (0)
; #define WAIT_V(n) asm volatile("s_waitcnt vmcnt(" #n ")" ::: "memory")
; #define WAIT_L(n) asm volatile("s_waitcnt lgkmcnt(" #n ")" ::: "memory")
; #define BAR __builtin_amdgcn_s_barrier()
;     ...
;       LDA(At, 0, 1); WAIT_V(4); BAR; WAIT_L(0); MMA(1, 0, At, B0); MMA(1, 1, At, B1); BAR; }
;     { LDB(B0, 1, 0); LDA(At, 1, 0); WAIT_V(2); BAR; WAIT_L(0); MMA(0, 0, At, B0); BAR;
	s_nop 1
	ds_read_b128 v[66:69], v133 offset:16384
	ds_read_b128 v[74:77], v133 offset:17408
	ds_read_b128 v[82:85], v134 offset:16384
	ds_read_b128 v[90:93], v134 offset:17408
	ds_read_b128 v[196:199], v137 offset:16384
	ds_read_b128 v[200:203], v137 offset:17408
	ds_read_b128 v[204:207], v139 offset:16384
	ds_read_b128 v[208:211], v139 offset:17408
	s_waitcnt vmcnt(4)
	s_barrier
	s_waitcnt lgkmcnt(0)
	s_setprio 1
	s_waitcnt lgkmcnt(0)
	v_mfma_f32_16x16x32_bf16 v[62:65], v[66:69], v[148:151], v[62:65]
	v_mfma_f32_16x16x32_bf16 v[54:57], v[82:85], v[148:151], v[54:57]
	v_mfma_f32_16x16x32_bf16 v[46:49], v[196:199], v[148:151], v[46:49]
	v_mfma_f32_16x16x32_bf16 v[38:41], v[204:207], v[148:151], v[38:41]
	v_mfma_f32_16x16x32_bf16 v[62:65], v[74:77], v[152:155], v[62:65]
	v_mfma_f32_16x16x32_bf16 v[58:61], v[66:69], v[156:159], v[58:61]
	v_mfma_f32_16x16x32_bf16 v[54:57], v[90:93], v[152:155], v[54:57]
	v_mfma_f32_16x16x32_bf16 v[50:53], v[82:85], v[156:159], v[50:53]
	v_mfma_f32_16x16x32_bf16 v[46:49], v[200:203], v[152:155], v[46:49]
	v_mfma_f32_16x16x32_bf16 v[42:45], v[196:199], v[156:159], v[42:45]
	v_mfma_f32_16x16x32_bf16 v[38:41], v[208:211], v[152:155], v[38:41]
	v_mfma_f32_16x16x32_bf16 v[34:37], v[204:207], v[156:159], v[34:37]
	v_mfma_f32_16x16x32_bf16 v[224:227], v[74:77], v[160:163], v[58:61]
	v_mfma_f32_16x16x32_bf16 v[228:231], v[90:93], v[160:163], v[50:53]
	v_mfma_f32_16x16x32_bf16 v[232:235], v[200:203], v[160:163], v[42:45]
	v_mfma_f32_16x16x32_bf16 v[148:151], v[208:211], v[160:163], v[34:37]
	s_setprio 0
	s_setprio 1
	v_mfma_f32_16x16x32_bf16 v[30:33], v[66:69], v[98:101], v[30:33]
	v_mfma_f32_16x16x32_bf16 v[22:25], v[82:85], v[98:101], v[22:25]
	v_mfma_f32_16x16x32_bf16 v[14:17], v[196:199], v[98:101], v[14:17]
	v_mfma_f32_16x16x32_bf16 v[6:9], v[204:207], v[98:101], v[6:9]
	v_mfma_f32_16x16x32_bf16 v[30:33], v[74:77], v[106:109], v[30:33]
	v_mfma_f32_16x16x32_bf16 v[26:29], v[66:69], v[114:117], v[26:29]
	v_mfma_f32_16x16x32_bf16 v[22:25], v[90:93], v[106:109], v[22:25]
	v_mfma_f32_16x16x32_bf16 v[18:21], v[82:85], v[114:117], v[18:21]
	v_mfma_f32_16x16x32_bf16 v[14:17], v[200:203], v[106:109], v[14:17]
	v_mfma_f32_16x16x32_bf16 v[10:13], v[196:199], v[114:117], v[10:13]
	v_mfma_f32_16x16x32_bf16 v[6:9], v[208:211], v[106:109], v[6:9]
	v_mfma_f32_16x16x32_bf16 v[2:5], v[204:207], v[114:117], v[2:5]
	v_mfma_f32_16x16x32_bf16 v[152:155], v[74:77], v[122:125], v[26:29]
	v_mfma_f32_16x16x32_bf16 v[156:159], v[90:93], v[122:125], v[18:21]
	v_mfma_f32_16x16x32_bf16 v[160:163], v[200:203], v[122:125], v[10:13]
	v_mfma_f32_16x16x32_bf16 v[196:199], v[208:211], v[122:125], v[2:5]
	s_setprio 0
	s_barrier
	s_nop 1
	ds_read_b128 v[2:5], v145
	ds_read_b128 v[10:13], v145 offset:1024
	ds_read_b128 v[200:203], v145 offset:2048
	ds_read_b128 v[204:207], v145 offset:3072
	ds_read_b128 v[18:21], v133 offset:32768
	ds_read_b128 v[26:29], v133 offset:33792
	ds_read_b128 v[34:37], v134 offset:32768
	ds_read_b128 v[42:45], v134 offset:33792
	ds_read_b128 v[50:53], v137 offset:32768
	ds_read_b128 v[58:61], v137 offset:33792
	ds_read_b128 v[208:211], v139 offset:32768
	ds_read_b128 v[236:239], v139 offset:33792
	s_waitcnt vmcnt(2)
	s_barrier
	s_waitcnt lgkmcnt(0)
	s_setprio 1
	s_waitcnt lgkmcnt(0)
	v_mfma_f32_16x16x32_bf16 v[66:69], v[18:21], v[2:5], v[126:129]
	v_mfma_f32_16x16x32_bf16 v[122:125], v[26:29], v[10:13], v[66:69]
	v_mfma_f32_16x16x32_bf16 v[66:69], v[18:21], v[200:203], v[140:143]
	v_mfma_f32_16x16x32_bf16 v[114:117], v[26:29], v[204:207], v[66:69]
	v_mfma_f32_16x16x32_bf16 v[66:69], v[34:37], v[2:5], v[118:121]
	v_mfma_f32_16x16x32_bf16 v[106:109], v[42:45], v[10:13], v[66:69]
	v_mfma_f32_16x16x32_bf16 v[66:69], v[34:37], v[200:203], v[212:215]
	v_mfma_f32_16x16x32_bf16 v[98:101], v[42:45], v[204:207], v[66:69]
	v_mfma_f32_16x16x32_bf16 v[66:69], v[50:53], v[2:5], v[110:113]
	v_mfma_f32_16x16x32_bf16 v[90:93], v[58:61], v[10:13], v[66:69]
	v_mfma_f32_16x16x32_bf16 v[66:69], v[50:53], v[200:203], v[216:219]
	v_mfma_f32_16x16x32_bf16 v[82:85], v[58:61], v[204:207], v[66:69]
	v_mfma_f32_16x16x32_bf16 v[66:69], v[208:211], v[2:5], v[102:105]
	v_mfma_f32_16x16x32_bf16 v[74:77], v[236:239], v[10:13], v[66:69]
	v_mfma_f32_16x16x32_bf16 v[66:69], v[208:211], v[200:203], v[220:223]
	v_mfma_f32_16x16x32_bf16 v[66:69], v[236:239], v[204:207], v[66:69]
	s_setprio 0
	s_barrier
; #define LDA(dst, b, h) for (int m = 0; m < 4; ++m) for (int k = 0; k < 2; ++k) \
;     dst[m][k] = *reinterpret_cast<const bf16x8*>((char*)SA(b, h) + lds_byte(wr * 64 + m * 16 + fr, k * 32 + fq * 8))
; #define LDB(dst, b, h) for (int n = 0; n < 2; ++n) for (int k = 0; k < 2; ++k) \
;     dst[n][k] = *reinterpret_cast<const bf16x8*>((char*)SB(b, h) + lds_byte(wc * 32 + n * 16 + fr, k * 32 + fq * 8))
; #define MMA(ai, bj, At, Bt_) do { __builtin_amdgcn_s_setprio(1); \
;     for (int m = 0; m < 4; ++m) for (int n = 0; n < 2; ++n) for (int k = 0; k < 2; ++k) \
;       acc[ai][bj][m][n] = __builtin_amdgcn_mfma_f32_16x16x32_bf16(At[m][k], Bt_[n][k], acc[ai][bj][m][n], 0, 0, 0); \
;     __builtin_amdgcn_s_setprio(0); } while (0)
; #define WAIT_V(n) asm volatile("s_waitcnt vmcnt(" #n ")" ::: "memory")
; #define WAIT_L(n) asm volatile("s_waitcnt lgkmcnt(" #n ")" ::: "memory")
; #define BAR __builtin_amdgcn_s_barrier()
;     ...
;       LDB(B1, 1, 1); WAIT_V(0); BAR; WAIT_L(0); MMA(0, 1, At, B1); BAR;
;       LDA(At, 1, 1); BAR; WAIT_L(0); MMA(1, 0, At, B0); MMA(1, 1, At, B1); BAR; }
;     if (wr == 0) BAR;
	ds_read_b128 v[140:143], v146
	ds_read_b128 v[212:215], v146 offset:1024
	ds_read_b128 v[216:219], v146 offset:2048
	ds_read_b128 v[144:147], v146 offset:3072
	s_waitcnt vmcnt(0)
	s_barrier
	s_waitcnt lgkmcnt(0)
	s_setprio 1
	s_waitcnt lgkmcnt(0)
	v_mfma_f32_16x16x32_bf16 v[94:97], v[18:21], v[140:143], v[94:97]
	v_mfma_f32_16x16x32_bf16 v[18:21], v[18:21], v[216:219], v[164:167]
	v_mfma_f32_16x16x32_bf16 v[118:121], v[26:29], v[144:147], v[18:21]
	v_mfma_f32_16x16x32_bf16 v[18:21], v[34:37], v[140:143], v[86:89]
	v_mfma_f32_16x16x32_bf16 v[110:113], v[42:45], v[212:215], v[18:21]
	v_mfma_f32_16x16x32_bf16 v[18:21], v[34:37], v[216:219], v[184:187]
	v_mfma_f32_16x16x32_bf16 v[102:105], v[42:45], v[144:147], v[18:21]
	v_mfma_f32_16x16x32_bf16 v[18:21], v[50:53], v[140:143], v[78:81]
	v_mfma_f32_16x16x32_bf16 v[126:129], v[26:29], v[212:215], v[94:97]
	v_mfma_f32_16x16x32_bf16 v[94:97], v[58:61], v[212:215], v[18:21]
	v_mfma_f32_16x16x32_bf16 v[18:21], v[50:53], v[216:219], v[188:191]
	v_mfma_f32_16x16x32_bf16 v[86:89], v[58:61], v[144:147], v[18:21]
	v_mfma_f32_16x16x32_bf16 v[18:21], v[208:211], v[140:143], v[70:73]
	v_mfma_f32_16x16x32_bf16 v[78:81], v[236:239], v[212:215], v[18:21]
	v_mfma_f32_16x16x32_bf16 v[18:21], v[208:211], v[216:219], v[192:195]
	v_mfma_f32_16x16x32_bf16 v[70:73], v[236:239], v[144:147], v[18:21]
	s_setprio 0
	s_barrier
	ds_read_b128 v[164:167], v133 offset:49152
	ds_read_b128 v[184:187], v133 offset:50176
	ds_read_b128 v[188:191], v134 offset:49152
	ds_read_b128 v[192:195], v134 offset:50176
	ds_read_b128 v[208:211], v137 offset:49152
	ds_read_b128 v[220:223], v137 offset:50176
	ds_read_b128 v[236:239], v139 offset:49152
	ds_read_b128 v[240:243], v139 offset:50176
	s_barrier
	s_waitcnt lgkmcnt(0)
	s_setprio 1
	s_waitcnt lgkmcnt(0)
	v_mfma_f32_16x16x32_bf16 v[18:21], v[164:167], v[2:5], v[62:65]
	v_mfma_f32_16x16x32_bf16 v[58:61], v[184:187], v[10:13], v[18:21]
	v_mfma_f32_16x16x32_bf16 v[18:21], v[164:167], v[200:203], v[224:227]
	v_mfma_f32_16x16x32_bf16 v[50:53], v[184:187], v[204:207], v[18:21]
	v_mfma_f32_16x16x32_bf16 v[18:21], v[188:191], v[2:5], v[54:57]
	v_mfma_f32_16x16x32_bf16 v[42:45], v[192:195], v[10:13], v[18:21]
	v_mfma_f32_16x16x32_bf16 v[18:21], v[188:191], v[200:203], v[228:231]
	v_mfma_f32_16x16x32_bf16 v[34:37], v[192:195], v[204:207], v[18:21]
	v_mfma_f32_16x16x32_bf16 v[18:21], v[208:211], v[2:5], v[46:49]
	v_mfma_f32_16x16x32_bf16 v[2:5], v[236:239], v[2:5], v[38:41]
	v_mfma_f32_16x16x32_bf16 v[26:29], v[220:223], v[10:13], v[18:21]
	v_mfma_f32_16x16x32_bf16 v[18:21], v[208:211], v[200:203], v[232:235]
	v_mfma_f32_16x16x32_bf16 v[10:13], v[240:243], v[10:13], v[2:5]
	v_mfma_f32_16x16x32_bf16 v[2:5], v[236:239], v[200:203], v[148:151]
	v_mfma_f32_16x16x32_bf16 v[18:21], v[220:223], v[204:207], v[18:21]
	v_mfma_f32_16x16x32_bf16 v[2:5], v[240:243], v[204:207], v[2:5]
	s_setprio 0
	s_setprio 1
	v_mfma_f32_16x16x32_bf16 v[30:33], v[164:167], v[140:143], v[30:33]
	v_mfma_f32_16x16x32_bf16 v[62:65], v[184:187], v[212:215], v[30:33]
	v_mfma_f32_16x16x32_bf16 v[30:33], v[164:167], v[216:219], v[152:155]
	v_mfma_f32_16x16x32_bf16 v[22:25], v[188:191], v[140:143], v[22:25]
	v_mfma_f32_16x16x32_bf16 v[14:17], v[208:211], v[140:143], v[14:17]
	v_mfma_f32_16x16x32_bf16 v[54:57], v[184:187], v[144:147], v[30:33]
	v_mfma_f32_16x16x32_bf16 v[46:49], v[192:195], v[212:215], v[22:25]
	v_mfma_f32_16x16x32_bf16 v[22:25], v[188:191], v[216:219], v[156:159]
	v_mfma_f32_16x16x32_bf16 v[30:33], v[220:223], v[212:215], v[14:17]
	v_mfma_f32_16x16x32_bf16 v[14:17], v[208:211], v[216:219], v[160:163]
	v_mfma_f32_16x16x32_bf16 v[6:9], v[236:239], v[140:143], v[6:9]
	v_mfma_f32_16x16x32_bf16 v[38:41], v[192:195], v[144:147], v[22:25]
	v_mfma_f32_16x16x32_bf16 v[22:25], v[220:223], v[144:147], v[14:17]
	v_mfma_f32_16x16x32_bf16 v[14:17], v[240:243], v[212:215], v[6:9]
	v_mfma_f32_16x16x32_bf16 v[6:9], v[236:239], v[216:219], v[196:199]
	v_mfma_f32_16x16x32_bf16 v[6:9], v[240:243], v[144:147], v[6:9]
	s_setprio 0
	v_readlane_b32 s4, v245, 33
	v_readlane_b32 s5, v245, 34
	s_and_b64 vcc, exec, s[4:5]
	s_barrier
	s_cbranch_vccz .LBB0_158
	s_barrier

; #define LDA(dst, b, h) for (int m = 0; m < 4; ++m) for (int k = 0; k < 2; ++k) \
;     dst[m][k] = *reinterpret_cast<const bf16x8*>((char*)SA(b, h) + lds_byte(wr * 64 + m * 16 + fr, k * 32 + fq * 8))
; #define LDB(dst, b, h) for (int n = 0; n < 2; ++n) for (int k = 0; k < 2; ++k) \
;     dst[n][k] = *reinterpret_cast<const bf16x8*>((char*)SB(b, h) + lds_byte(wc * 32 + n * 16 + fr, k * 32 + fq * 8))
; #define MMA(ai, bj, At, Bt_) do { __builtin_amdgcn_s_setprio(1); \
;     for (int m = 0; m < 4; ++m) for (int n = 0; n < 2; ++n) for (int k = 0; k < 2; ++k) \
;       acc[ai][bj][m][n] = __builtin_amdgcn_mfma_f32_16x16x32_bf16(At[m][k], Bt_[n][k], acc[ai][bj][m][n], 0, 0, 0); \
;     __builtin_amdgcn_s_setprio(0); } while (0)
; #define WAIT_L(n) asm volatile("s_waitcnt lgkmcnt(" #n ")" ::: "memory")
; #define BAR __builtin_amdgcn_s_barrier()
; #define SCHED __builtin_amdgcn_sched_barrier(0)
;     ...
;       LDB(B0, 0, 0); SCHED; LDA(At, 0, 0); STAGE(SA(1, 1), A, brow + HALF, t + 1);
;       WAIT_L(8); BAR; WAIT_L(0); MMA(0, 0, At, B0); BAR; SCHED;
;       LDB(B1, 0, 1); STAGE(SB(0, 0), Bt, bcol, t + 2);
;       BAR; WAIT_L(0); MMA(0, 1, At, B1); BAR;
;       LDA(At, 0, 1); STAGE(SA(0, 0), A, brow, t + 2);
;       BAR; WAIT_L(0); MMA(1, 0, At, B0); BAR; SCHED;
.LBB0_202:
	v_add_u32_e32 v143, s2, v142
	ds_read_b128 v[146:149], v143
	ds_read_b128 v[150:153], v143 offset:1024
	ds_read_b128 v[154:157], v143 offset:2048
	ds_read_b128 v[158:161], v143 offset:3072
	s_add_u32 s66, s50, s16
	s_addc_u32 s67, s51, s17
	s_add_i32 s58, s21, 0xc000
	ds_read_b128 v[162:165], v133
	ds_read_b128 v[184:187], v133 offset:1024
	ds_read_b128 v[188:191], v134
	ds_read_b128 v[192:195], v134 offset:1024
	ds_read_b128 v[196:199], v137
	ds_read_b128 v[200:203], v137 offset:1024
	ds_read_b128 v[204:207], v139
	ds_read_b128 v[208:211], v139 offset:1024
	s_mov_b32 m0, s58
	v_lshl_add_u64 v[144:145], s[66:67], 0, v[0:1]
	s_add_i32 s57, s21, 0xe000
	global_load_lds_dwordx4 v[144:145], off
	v_lshl_add_u64 v[144:145], s[66:67], 0, v[140:141]
	s_mov_b32 m0, s57
	s_nop 0
	global_load_lds_dwordx4 v[144:145], off
	s_waitcnt lgkmcnt(8)
	s_barrier
	s_waitcnt lgkmcnt(0)
	s_setprio 0
	s_waitcnt lgkmcnt(0)
	v_mfma_f32_16x16x32_bf16 v[126:129], v[162:165], v[146:149], v[126:129]
	v_mfma_f32_16x16x32_bf16 v[122:125], v[162:165], v[154:157], v[122:125]
	v_mfma_f32_16x16x32_bf16 v[118:121], v[188:191], v[146:149], v[118:121]
	v_mfma_f32_16x16x32_bf16 v[114:117], v[188:191], v[154:157], v[114:117]
	v_mfma_f32_16x16x32_bf16 v[110:113], v[196:199], v[146:149], v[110:113]
	v_mfma_f32_16x16x32_bf16 v[106:109], v[196:199], v[154:157], v[106:109]
	v_mfma_f32_16x16x32_bf16 v[102:105], v[204:207], v[146:149], v[102:105]
	v_mfma_f32_16x16x32_bf16 v[98:101], v[204:207], v[154:157], v[98:101]
	v_mfma_f32_16x16x32_bf16 v[126:129], v[184:187], v[150:153], v[126:129]
	v_mfma_f32_16x16x32_bf16 v[122:125], v[184:187], v[158:161], v[122:125]
	v_mfma_f32_16x16x32_bf16 v[118:121], v[192:195], v[150:153], v[118:121]
	v_mfma_f32_16x16x32_bf16 v[114:117], v[192:195], v[158:161], v[114:117]
	v_mfma_f32_16x16x32_bf16 v[110:113], v[200:203], v[150:153], v[110:113]
	v_mfma_f32_16x16x32_bf16 v[106:109], v[200:203], v[158:161], v[106:109]
	v_mfma_f32_16x16x32_bf16 v[102:105], v[208:211], v[150:153], v[102:105]
	v_mfma_f32_16x16x32_bf16 v[98:101], v[208:211], v[158:161], v[98:101]
	s_setprio 1
	s_barrier
	s_add_i32 s55, s55, 2
	s_add_u32 s59, s11, s16
	s_addc_u32 s63, s44, s17
	s_add_u32 s66, s59, 0x100
	v_add_u32_e32 v144, s76, v142
	s_addc_u32 s67, s63, 0
	s_mov_b32 m0, s29
	ds_read_b128 v[212:215], v144
	ds_read_b128 v[216:219], v144 offset:1024
	ds_read_b128 v[220:223], v144 offset:2048
	ds_read_b128 v[224:227], v144 offset:3072
	s_nop 0
	v_lshl_add_u64 v[166:167], s[66:67], 0, v[0:1]
	global_load_lds_dwordx4 v[166:167], off
	v_lshl_add_u64 v[166:167], s[66:67], 0, v[140:141]
	s_mov_b32 m0, s30
	s_nop 0
	global_load_lds_dwordx4 v[166:167], off
	s_barrier
	s_waitcnt lgkmcnt(0)
	s_setprio 0
	s_waitcnt lgkmcnt(0)
	v_mfma_f32_16x16x32_bf16 v[94:97], v[162:165], v[212:215], v[94:97]
	v_mfma_f32_16x16x32_bf16 v[90:93], v[162:165], v[220:223], v[90:93]
	v_mfma_f32_16x16x32_bf16 v[86:89], v[188:191], v[212:215], v[86:89]
	v_mfma_f32_16x16x32_bf16 v[82:85], v[188:191], v[220:223], v[82:85]
	v_mfma_f32_16x16x32_bf16 v[78:81], v[196:199], v[212:215], v[78:81]
	v_mfma_f32_16x16x32_bf16 v[74:77], v[196:199], v[220:223], v[74:77]
	v_mfma_f32_16x16x32_bf16 v[70:73], v[204:207], v[212:215], v[70:73]
	v_mfma_f32_16x16x32_bf16 v[66:69], v[204:207], v[220:223], v[66:69]
	v_mfma_f32_16x16x32_bf16 v[94:97], v[184:187], v[216:219], v[94:97]
	v_mfma_f32_16x16x32_bf16 v[90:93], v[184:187], v[224:227], v[90:93]
	v_mfma_f32_16x16x32_bf16 v[86:89], v[192:195], v[216:219], v[86:89]
	v_mfma_f32_16x16x32_bf16 v[82:85], v[192:195], v[224:227], v[82:85]
	v_mfma_f32_16x16x32_bf16 v[78:81], v[200:203], v[216:219], v[78:81]
	v_mfma_f32_16x16x32_bf16 v[74:77], v[200:203], v[224:227], v[74:77]
	v_mfma_f32_16x16x32_bf16 v[70:73], v[208:211], v[216:219], v[70:73]
	v_mfma_f32_16x16x32_bf16 v[66:69], v[208:211], v[224:227], v[66:69]
	s_setprio 1
	s_add_u32 s65, s13, s16
	s_addc_u32 s70, s45, s17
	s_add_u32 s66, s65, 0x100
	s_addc_u32 s67, s70, 0
	s_mov_b32 m0, s21
	s_barrier
	ds_read_b128 v[162:165], v133 offset:16384
	ds_read_b128 v[184:187], v133 offset:17408
	ds_read_b128 v[188:191], v134 offset:16384
	ds_read_b128 v[192:195], v134 offset:17408
	ds_read_b128 v[196:199], v137 offset:16384
	ds_read_b128 v[200:203], v137 offset:17408
	ds_read_b128 v[204:207], v139 offset:16384
	ds_read_b128 v[208:211], v139 offset:17408
	s_nop 0
	v_lshl_add_u64 v[166:167], s[66:67], 0, v[0:1]
	global_load_lds_dwordx4 v[166:167], off
	v_lshl_add_u64 v[166:167], s[66:67], 0, v[140:141]
	s_mov_b32 m0, s31
	s_nop 0
	global_load_lds_dwordx4 v[166:167], off
	s_barrier
	s_waitcnt lgkmcnt(0)
	s_setprio 0
	s_waitcnt lgkmcnt(0)
	v_mfma_f32_16x16x32_bf16 v[62:65], v[162:165], v[146:149], v[62:65]
	v_mfma_f32_16x16x32_bf16 v[58:61], v[162:165], v[154:157], v[58:61]
	v_mfma_f32_16x16x32_bf16 v[54:57], v[188:191], v[146:149], v[54:57]
	v_mfma_f32_16x16x32_bf16 v[50:53], v[188:191], v[154:157], v[50:53]
	v_mfma_f32_16x16x32_bf16 v[46:49], v[196:199], v[146:149], v[46:49]
	v_mfma_f32_16x16x32_bf16 v[42:45], v[196:199], v[154:157], v[42:45]
	v_mfma_f32_16x16x32_bf16 v[38:41], v[204:207], v[146:149], v[38:41]
	v_mfma_f32_16x16x32_bf16 v[34:37], v[204:207], v[154:157], v[34:37]
	v_mfma_f32_16x16x32_bf16 v[62:65], v[184:187], v[150:153], v[62:65]
	v_mfma_f32_16x16x32_bf16 v[58:61], v[184:187], v[158:161], v[58:61]
	v_mfma_f32_16x16x32_bf16 v[54:57], v[192:195], v[150:153], v[54:57]
	v_mfma_f32_16x16x32_bf16 v[50:53], v[192:195], v[158:161], v[50:53]
	v_mfma_f32_16x16x32_bf16 v[46:49], v[200:203], v[150:153], v[46:49]
	v_mfma_f32_16x16x32_bf16 v[42:45], v[200:203], v[158:161], v[42:45]
	v_mfma_f32_16x16x32_bf16 v[38:41], v[208:211], v[150:153], v[38:41]
	v_mfma_f32_16x16x32_bf16 v[34:37], v[208:211], v[158:161], v[34:37]
	s_setprio 1
	s_barrier
; #define LDA(dst, b, h) for (int m = 0; m < 4; ++m) for (int k = 0; k < 2; ++k) \
;     dst[m][k] = *reinterpret_cast<const bf16x8*>((char*)SA(b, h) + lds_byte(wr * 64 + m * 16 + fr, k * 32 + fq * 8))
; #define LDB(dst, b, h) for (int n = 0; n < 2; ++n) for (int k = 0; k < 2; ++k) \
;     dst[n][k] = *reinterpret_cast<const bf16x8*>((char*)SB(b, h) + lds_byte(wc * 32 + n * 16 + fr, k * 32 + fq * 8))
; #define MMA(ai, bj, At, Bt_) do { __builtin_amdgcn_s_setprio(1); \
;     for (int m = 0; m < 4; ++m) for (int n = 0; n < 2; ++n) for (int k = 0; k < 2; ++k) \
;       acc[ai][bj][m][n] = __builtin_amdgcn_mfma_f32_16x16x32_bf16(At[m][k], Bt_[n][k], acc[ai][bj][m][n], 0, 0, 0); \
;     __builtin_amdgcn_s_setprio(0); } while (0)
; #define WAIT_V(n) asm volatile("s_waitcnt vmcnt(" #n ")" ::: "memory")
; #define WAIT_L(n) asm volatile("s_waitcnt lgkmcnt(" #n ")" ::: "memory")
; #define BAR __builtin_amdgcn_s_barrier()
; #define SCHED __builtin_amdgcn_sched_barrier(0)
;     ...
;       STAGE(SB(0, 1), Bt, bcol + HALF, t + 2);
;       WAIT_V(6); BAR; MMA(1, 1, At, B1); BAR;
;       LDB(B0, 1, 0); SCHED; LDA(At, 1, 0); STAGE(SA(0, 1), A, brow + HALF, t + 2);
;       WAIT_L(8); BAR; WAIT_L(0); MMA(0, 0, At, B0); BAR; SCHED;
;       LDB(B1, 1, 1); STAGE(SB(1, 0), Bt, bcol, t + 3);
;       BAR; WAIT_L(0); MMA(0, 1, At, B1); BAR;
;       LDA(At, 1, 1); STAGE(SA(1, 0), A, brow, t + 3);
	s_add_u32 s66, s59, 0x80100
	s_addc_u32 s67, s63, 0
	s_mov_b32 m0, s34
	s_nop 0
	v_lshl_add_u64 v[146:147], s[66:67], 0, v[0:1]
	global_load_lds_dwordx4 v[146:147], off
	v_lshl_add_u64 v[146:147], s[66:67], 0, v[140:141]
	s_mov_b32 m0, s35
	s_nop 0
	global_load_lds_dwordx4 v[146:147], off
	s_waitcnt vmcnt(6)
	s_barrier
	s_setprio 0
	v_mfma_f32_16x16x32_bf16 v[30:33], v[162:165], v[212:215], v[30:33]
	v_mfma_f32_16x16x32_bf16 v[26:29], v[162:165], v[220:223], v[26:29]
	v_mfma_f32_16x16x32_bf16 v[22:25], v[188:191], v[212:215], v[22:25]
	v_mfma_f32_16x16x32_bf16 v[18:21], v[188:191], v[220:223], v[18:21]
	v_mfma_f32_16x16x32_bf16 v[14:17], v[196:199], v[212:215], v[14:17]
	v_mfma_f32_16x16x32_bf16 v[10:13], v[196:199], v[220:223], v[10:13]
	v_mfma_f32_16x16x32_bf16 v[6:9], v[204:207], v[212:215], v[6:9]
	v_mfma_f32_16x16x32_bf16 v[2:5], v[204:207], v[220:223], v[2:5]
	v_mfma_f32_16x16x32_bf16 v[30:33], v[184:187], v[216:219], v[30:33]
	v_mfma_f32_16x16x32_bf16 v[26:29], v[184:187], v[224:227], v[26:29]
	v_mfma_f32_16x16x32_bf16 v[22:25], v[192:195], v[216:219], v[22:25]
	v_mfma_f32_16x16x32_bf16 v[18:21], v[192:195], v[224:227], v[18:21]
	v_mfma_f32_16x16x32_bf16 v[14:17], v[200:203], v[216:219], v[14:17]
	v_mfma_f32_16x16x32_bf16 v[10:13], v[200:203], v[224:227], v[10:13]
	v_mfma_f32_16x16x32_bf16 v[6:9], v[208:211], v[216:219], v[6:9]
	v_mfma_f32_16x16x32_bf16 v[2:5], v[208:211], v[224:227], v[2:5]
	s_setprio 1
	v_add_u32_e32 v145, s77, v142
	s_barrier
	ds_read_b128 v[148:151], v145
	ds_read_b128 v[152:155], v145 offset:1024
	ds_read_b128 v[156:159], v145 offset:2048
	ds_read_b128 v[160:163], v145 offset:3072
	s_add_u32 s66, s65, 0x80100
	s_addc_u32 s67, s70, 0
	s_mov_b32 m0, s37
	ds_read_b128 v[164:167], v133 offset:32768
	ds_read_b128 v[184:187], v133 offset:33792
	ds_read_b128 v[188:191], v134 offset:32768
	ds_read_b128 v[192:195], v134 offset:33792
	ds_read_b128 v[196:199], v137 offset:32768
	ds_read_b128 v[200:203], v137 offset:33792
	ds_read_b128 v[204:207], v139 offset:32768
	ds_read_b128 v[208:211], v139 offset:33792
	s_nop 0
	v_lshl_add_u64 v[146:147], s[66:67], 0, v[0:1]
	global_load_lds_dwordx4 v[146:147], off
	v_lshl_add_u64 v[146:147], s[66:67], 0, v[140:141]
	s_mov_b32 m0, s38
	s_nop 0
	global_load_lds_dwordx4 v[146:147], off
	s_waitcnt lgkmcnt(8)
	s_barrier
	s_waitcnt lgkmcnt(0)
	s_setprio 0
	s_waitcnt lgkmcnt(0)
	v_mfma_f32_16x16x32_bf16 v[126:129], v[164:167], v[148:151], v[126:129]
	v_mfma_f32_16x16x32_bf16 v[122:125], v[164:167], v[156:159], v[122:125]
	v_mfma_f32_16x16x32_bf16 v[118:121], v[188:191], v[148:151], v[118:121]
	v_mfma_f32_16x16x32_bf16 v[114:117], v[188:191], v[156:159], v[114:117]
	v_mfma_f32_16x16x32_bf16 v[110:113], v[196:199], v[148:151], v[110:113]
	v_mfma_f32_16x16x32_bf16 v[106:109], v[196:199], v[156:159], v[106:109]
	v_mfma_f32_16x16x32_bf16 v[102:105], v[204:207], v[148:151], v[102:105]
	v_mfma_f32_16x16x32_bf16 v[98:101], v[204:207], v[156:159], v[98:101]
	v_mfma_f32_16x16x32_bf16 v[126:129], v[184:187], v[152:155], v[126:129]
	v_mfma_f32_16x16x32_bf16 v[122:125], v[184:187], v[160:163], v[122:125]
	v_mfma_f32_16x16x32_bf16 v[118:121], v[192:195], v[152:155], v[118:121]
	v_mfma_f32_16x16x32_bf16 v[114:117], v[192:195], v[160:163], v[114:117]
	v_mfma_f32_16x16x32_bf16 v[110:113], v[200:203], v[152:155], v[110:113]
	v_mfma_f32_16x16x32_bf16 v[106:109], v[200:203], v[160:163], v[106:109]
	v_mfma_f32_16x16x32_bf16 v[102:105], v[208:211], v[152:155], v[102:105]
	v_mfma_f32_16x16x32_bf16 v[98:101], v[208:211], v[160:163], v[98:101]
	s_setprio 1
	s_barrier
	s_add_u32 s66, s59, 0x180
	v_add_u32_e32 v146, s78, v142
	s_addc_u32 s67, s63, 0
	s_mov_b32 m0, s39
	ds_read_b128 v[212:215], v146
	ds_read_b128 v[216:219], v146 offset:1024
	ds_read_b128 v[220:223], v146 offset:2048
	ds_read_b128 v[224:227], v146 offset:3072
	s_nop 0
	v_lshl_add_u64 v[228:229], s[66:67], 0, v[0:1]
	global_load_lds_dwordx4 v[228:229], off
	v_lshl_add_u64 v[228:229], s[66:67], 0, v[140:141]
	s_mov_b32 m0, s40
	s_nop 0
	global_load_lds_dwordx4 v[228:229], off
	s_barrier
	s_waitcnt lgkmcnt(0)
	s_setprio 0
	s_waitcnt lgkmcnt(0)
	v_mfma_f32_16x16x32_bf16 v[94:97], v[164:167], v[212:215], v[94:97]
	v_mfma_f32_16x16x32_bf16 v[90:93], v[164:167], v[220:223], v[90:93]
	v_mfma_f32_16x16x32_bf16 v[86:89], v[188:191], v[212:215], v[86:89]
	v_mfma_f32_16x16x32_bf16 v[82:85], v[188:191], v[220:223], v[82:85]
	v_mfma_f32_16x16x32_bf16 v[78:81], v[196:199], v[212:215], v[78:81]
	v_mfma_f32_16x16x32_bf16 v[74:77], v[196:199], v[220:223], v[74:77]
	v_mfma_f32_16x16x32_bf16 v[70:73], v[204:207], v[212:215], v[70:73]
	v_mfma_f32_16x16x32_bf16 v[66:69], v[204:207], v[220:223], v[66:69]
	v_mfma_f32_16x16x32_bf16 v[94:97], v[184:187], v[216:219], v[94:97]
	v_mfma_f32_16x16x32_bf16 v[90:93], v[184:187], v[224:227], v[90:93]
	v_mfma_f32_16x16x32_bf16 v[86:89], v[192:195], v[216:219], v[86:89]
	v_mfma_f32_16x16x32_bf16 v[82:85], v[192:195], v[224:227], v[82:85]
	v_mfma_f32_16x16x32_bf16 v[78:81], v[200:203], v[216:219], v[78:81]
	v_mfma_f32_16x16x32_bf16 v[74:77], v[200:203], v[224:227], v[74:77]
	v_mfma_f32_16x16x32_bf16 v[70:73], v[208:211], v[216:219], v[70:73]
	v_mfma_f32_16x16x32_bf16 v[66:69], v[208:211], v[224:227], v[66:69]
	s_setprio 1
	s_add_u32 s66, s65, 0x180
	s_addc_u32 s67, s70, 0
	s_mov_b32 m0, s41
	s_barrier
	ds_read_b128 v[164:167], v133 offset:49152
	ds_read_b128 v[184:187], v133 offset:50176
	ds_read_b128 v[188:191], v134 offset:49152
	ds_read_b128 v[192:195], v134 offset:50176
	ds_read_b128 v[196:199], v137 offset:49152
	ds_read_b128 v[200:203], v137 offset:50176
	ds_read_b128 v[204:207], v139 offset:49152
	ds_read_b128 v[208:211], v139 offset:50176
	s_nop 0
	v_lshl_add_u64 v[228:229], s[66:67], 0, v[0:1]
	global_load_lds_dwordx4 v[228:229], off
	v_lshl_add_u64 v[228:229], s[66:67], 0, v[140:141]
	s_mov_b32 m0, s42
	s_nop 0
	global_load_lds_dwordx4 v[228:229], off
	s_barrier
; #define LDA(dst, b, h) for (int m = 0; m < 4; ++m) for (int k = 0; k < 2; ++k) \
;     dst[m][k] = *reinterpret_cast<const bf16x8*>((char*)SA(b, h) + lds_byte(wr * 64 + m * 16 + fr, k * 32 + fq * 8))
; #define LDB(dst, b, h) for (int n = 0; n < 2; ++n) for (int k = 0; k < 2; ++k) \
;     dst[n][k] = *reinterpret_cast<const bf16x8*>((char*)SB(b, h) + lds_byte(wc * 32 + n * 16 + fr, k * 32 + fq * 8))
; #define MMA(ai, bj, At, Bt_) do { __builtin_amdgcn_s_setprio(1); \
;     for (int m = 0; m < 4; ++m) for (int n = 0; n < 2; ++n) for (int k = 0; k < 2; ++k) \
;       acc[ai][bj][m][n] = __builtin_amdgcn_mfma_f32_16x16x32_bf16(At[m][k], Bt_[n][k], acc[ai][bj][m][n], 0, 0, 0); \
;     __builtin_amdgcn_s_setprio(0); } while (0)
; #define WAIT_V(n) asm volatile("s_waitcnt vmcnt(" #n ")" ::: "memory")
; #define WAIT_L(n) asm volatile("s_waitcnt lgkmcnt(" #n ")" ::: "memory")
; #define BAR __builtin_amdgcn_s_barrier()
; #define SCHED __builtin_amdgcn_sched_barrier(0)
;     ...
;       BAR; WAIT_L(0); MMA(1, 0, At, B0); BAR; SCHED;
;       STAGE(SB(1, 1), Bt, bcol + HALF, t + 3);
;       WAIT_V(6); BAR; MMA(1, 1, At, B1); BAR;
;     }
;     { LDB(B0, 0, 0); LDA(At, 0, 0); STAGE(SA(1, 1), A, brow + HALF, nt - 1);
;       BAR; WAIT_L(0); MMA(0, 0, At, B0); BAR;
;       LDB(B1, 0, 1); BAR; WAIT_L(0); MMA(0, 1, At, B1); BAR;
	s_waitcnt lgkmcnt(0)
	s_setprio 0
	s_waitcnt lgkmcnt(0)
	v_mfma_f32_16x16x32_bf16 v[62:65], v[164:167], v[148:151], v[62:65]
	v_mfma_f32_16x16x32_bf16 v[58:61], v[164:167], v[156:159], v[58:61]
	v_mfma_f32_16x16x32_bf16 v[54:57], v[188:191], v[148:151], v[54:57]
	v_mfma_f32_16x16x32_bf16 v[50:53], v[188:191], v[156:159], v[50:53]
	v_mfma_f32_16x16x32_bf16 v[46:49], v[196:199], v[148:151], v[46:49]
	v_mfma_f32_16x16x32_bf16 v[42:45], v[196:199], v[156:159], v[42:45]
	v_mfma_f32_16x16x32_bf16 v[38:41], v[204:207], v[148:151], v[38:41]
	v_mfma_f32_16x16x32_bf16 v[34:37], v[204:207], v[156:159], v[34:37]
	v_mfma_f32_16x16x32_bf16 v[62:65], v[184:187], v[152:155], v[62:65]
	v_mfma_f32_16x16x32_bf16 v[58:61], v[184:187], v[160:163], v[58:61]
	v_mfma_f32_16x16x32_bf16 v[54:57], v[192:195], v[152:155], v[54:57]
	v_mfma_f32_16x16x32_bf16 v[50:53], v[192:195], v[160:163], v[50:53]
	v_mfma_f32_16x16x32_bf16 v[46:49], v[200:203], v[152:155], v[46:49]
	v_mfma_f32_16x16x32_bf16 v[42:45], v[200:203], v[160:163], v[42:45]
	v_mfma_f32_16x16x32_bf16 v[38:41], v[208:211], v[152:155], v[38:41]
	v_mfma_f32_16x16x32_bf16 v[34:37], v[208:211], v[160:163], v[34:37]
	s_setprio 1
	s_barrier
	s_add_u32 s66, s59, 0x80180
	s_addc_u32 s67, s63, 0
	s_mov_b32 m0, s18
	s_nop 0
	v_lshl_add_u64 v[148:149], s[66:67], 0, v[0:1]
	global_load_lds_dwordx4 v[148:149], off
	v_lshl_add_u64 v[148:149], s[66:67], 0, v[140:141]
	s_mov_b32 m0, s19
	s_nop 0
	global_load_lds_dwordx4 v[148:149], off
	s_waitcnt vmcnt(6)
	s_barrier
	s_setprio 0
	v_mfma_f32_16x16x32_bf16 v[30:33], v[164:167], v[212:215], v[30:33]
	v_mfma_f32_16x16x32_bf16 v[26:29], v[164:167], v[220:223], v[26:29]
	v_mfma_f32_16x16x32_bf16 v[22:25], v[188:191], v[212:215], v[22:25]
	v_mfma_f32_16x16x32_bf16 v[18:21], v[188:191], v[220:223], v[18:21]
	v_mfma_f32_16x16x32_bf16 v[14:17], v[196:199], v[212:215], v[14:17]
	v_mfma_f32_16x16x32_bf16 v[10:13], v[196:199], v[220:223], v[10:13]
	v_mfma_f32_16x16x32_bf16 v[6:9], v[204:207], v[212:215], v[6:9]
	v_mfma_f32_16x16x32_bf16 v[2:5], v[204:207], v[220:223], v[2:5]
	v_mfma_f32_16x16x32_bf16 v[30:33], v[184:187], v[216:219], v[30:33]
	v_mfma_f32_16x16x32_bf16 v[26:29], v[184:187], v[224:227], v[26:29]
	v_mfma_f32_16x16x32_bf16 v[22:25], v[192:195], v[216:219], v[22:25]
	v_mfma_f32_16x16x32_bf16 v[18:21], v[192:195], v[224:227], v[18:21]
	v_mfma_f32_16x16x32_bf16 v[14:17], v[200:203], v[216:219], v[14:17]
	v_mfma_f32_16x16x32_bf16 v[10:13], v[200:203], v[224:227], v[10:13]
	v_mfma_f32_16x16x32_bf16 v[6:9], v[208:211], v[216:219], v[6:9]
	v_mfma_f32_16x16x32_bf16 v[2:5], v[208:211], v[224:227], v[2:5]
	s_setprio 1
	s_add_u32 s11, s11, 0x100
	s_addc_u32 s44, s44, 0
	s_add_u32 s13, s13, 0x100
	s_addc_u32 s45, s45, 0
	s_add_u32 s50, s50, 0x100
	s_addc_u32 s51, s51, 0
	s_cmp_ge_u32 s55, s43
	s_barrier
	s_cbranch_scc0 .LBB0_202
	s_setprio 0
	s_add_i32 s11, s48, s20
	s_add_i32 s48, s11, -1
	s_lshl_b64 s[16:17], s[48:49], 7
	s_add_u32 s11, s74, s16
	s_addc_u32 s13, s75, s17
	s_add_u32 s4, s11, s4
	s_addc_u32 s5, s13, s5
	s_mov_b32 m0, s58
	ds_read_b128 v[148:151], v143
	ds_read_b128 v[152:155], v143 offset:1024
	ds_read_b128 v[156:159], v143 offset:2048
	ds_read_b128 v[160:163], v143 offset:3072
	ds_read_b128 v[164:167], v133
	ds_read_b128 v[184:187], v133 offset:1024
	ds_read_b128 v[188:191], v134
	ds_read_b128 v[192:195], v134 offset:1024
	ds_read_b128 v[196:199], v137
	ds_read_b128 v[200:203], v137 offset:1024
	ds_read_b128 v[204:207], v139
	ds_read_b128 v[208:211], v139 offset:1024
	s_nop 0
	v_lshl_add_u64 v[142:143], s[4:5], 0, v[0:1]
	global_load_lds_dwordx4 v[142:143], off
	v_lshl_add_u64 v[140:141], s[4:5], 0, v[140:141]
	s_mov_b32 m0, s57
	s_nop 0
	global_load_lds_dwordx4 v[140:141], off
	s_barrier
	s_waitcnt lgkmcnt(0)
	s_setprio 1
	s_waitcnt lgkmcnt(0)
	v_mfma_f32_16x16x32_bf16 v[126:129], v[164:167], v[148:151], v[126:129]
	v_mfma_f32_16x16x32_bf16 v[122:125], v[164:167], v[156:159], v[122:125]
	v_mfma_f32_16x16x32_bf16 v[118:121], v[188:191], v[148:151], v[118:121]
	v_mfma_f32_16x16x32_bf16 v[110:113], v[196:199], v[148:151], v[110:113]
	v_mfma_f32_16x16x32_bf16 v[106:109], v[196:199], v[156:159], v[106:109]
	v_mfma_f32_16x16x32_bf16 v[102:105], v[204:207], v[148:151], v[102:105]
	v_mfma_f32_16x16x32_bf16 v[98:101], v[204:207], v[156:159], v[98:101]
	v_mfma_f32_16x16x32_bf16 v[126:129], v[184:187], v[152:155], v[126:129]
	v_mfma_f32_16x16x32_bf16 v[122:125], v[184:187], v[160:163], v[122:125]
	v_mfma_f32_16x16x32_bf16 v[118:121], v[192:195], v[152:155], v[118:121]
	v_mfma_f32_16x16x32_bf16 v[114:117], v[188:191], v[156:159], v[114:117]
	v_mfma_f32_16x16x32_bf16 v[110:113], v[200:203], v[152:155], v[110:113]
	v_mfma_f32_16x16x32_bf16 v[106:109], v[200:203], v[160:163], v[106:109]
	v_mfma_f32_16x16x32_bf16 v[102:105], v[208:211], v[152:155], v[102:105]
	v_mfma_f32_16x16x32_bf16 v[98:101], v[208:211], v[160:163], v[98:101]
	v_mfma_f32_16x16x32_bf16 v[140:143], v[192:195], v[160:163], v[114:117]
	s_setprio 0
	s_barrier
	s_nop 0
	ds_read_b128 v[114:117], v144
	ds_read_b128 v[212:215], v144 offset:1024
	ds_read_b128 v[216:219], v144 offset:2048
	ds_read_b128 v[220:223], v144 offset:3072
	s_barrier
; #define LDA(dst, b, h) for (int m = 0; m < 4; ++m) for (int k = 0; k < 2; ++k) \
;     dst[m][k] = *reinterpret_cast<const bf16x8*>((char*)SA(b, h) + lds_byte(wr * 64 + m * 16 + fr, k * 32 + fq * 8))
; #define LDB(dst, b, h) for (int n = 0; n < 2; ++n) for (int k = 0; k < 2; ++k) \
;     dst[n][k] = *reinterpret_cast<const bf16x8*>((char*)SB(b, h) + lds_byte(wc * 32 + n * 16 + fr, k * 32 + fq * 8))
; #define MMA(ai, bj, At, Bt_) do { __builtin_amdgcn_s_setprio(1); \
;     for (int m = 0; m < 4; ++m) for (int n = 0; n < 2; ++n) for (int k = 0; k < 2; ++k) \
;       acc[ai][bj][m][n] = __builtin_amdgcn_mfma_f32_16x16x32_bf16(At[m][k], Bt_[n][k], acc[ai][bj][m][n], 0, 0, 0); \
;     __builtin_amdgcn_s_setprio(0); } while (0)
; #define WAIT_V(n) asm volatile("s_waitcnt vmcnt(" #n ")" ::: "memory")
; #define WAIT_L(n) asm volatile("s_waitcnt lgkmcnt(" #n ")" ::: "memory")
; #define BAR __builtin_amdgcn_s_barrier()
;     ...
;       LDB(B1, 0, 1); BAR; WAIT_L(0); MMA(0, 1, At, B1); BAR;
;       LDA(At, 0, 1); WAIT_V(4); BAR; WAIT_L(0); MMA(1, 0, At, B0); MMA(1, 1, At, B1); BAR; }
;     { LDB(B0, 1, 0); LDA(At, 1, 0); WAIT_V(2); BAR; WAIT_L(0); MMA(0, 0, At, B0); BAR;
	s_waitcnt lgkmcnt(0)
	s_setprio 1
	s_waitcnt lgkmcnt(0)
	v_mfma_f32_16x16x32_bf16 v[90:93], v[164:167], v[216:219], v[90:93]
	v_mfma_f32_16x16x32_bf16 v[86:89], v[188:191], v[114:117], v[86:89]
	v_mfma_f32_16x16x32_bf16 v[94:97], v[164:167], v[114:117], v[94:97]
	v_mfma_f32_16x16x32_bf16 v[90:93], v[184:187], v[220:223], v[90:93]
	v_mfma_f32_16x16x32_bf16 v[86:89], v[192:195], v[212:215], v[86:89]
	v_mfma_f32_16x16x32_bf16 v[82:85], v[188:191], v[216:219], v[82:85]
	v_mfma_f32_16x16x32_bf16 v[78:81], v[196:199], v[114:117], v[78:81]
	v_mfma_f32_16x16x32_bf16 v[74:77], v[196:199], v[216:219], v[74:77]
	v_mfma_f32_16x16x32_bf16 v[70:73], v[204:207], v[114:117], v[70:73]
	v_mfma_f32_16x16x32_bf16 v[66:69], v[204:207], v[216:219], v[66:69]
	v_mfma_f32_16x16x32_bf16 v[224:227], v[184:187], v[212:215], v[94:97]
	v_mfma_f32_16x16x32_bf16 v[164:167], v[192:195], v[220:223], v[82:85]
	v_mfma_f32_16x16x32_bf16 v[184:187], v[200:203], v[212:215], v[78:81]
	v_mfma_f32_16x16x32_bf16 v[188:191], v[200:203], v[220:223], v[74:77]
	v_mfma_f32_16x16x32_bf16 v[192:195], v[208:211], v[212:215], v[70:73]
	v_mfma_f32_16x16x32_bf16 v[196:199], v[208:211], v[220:223], v[66:69]
	s_setprio 0
	s_barrier
	s_nop 0
	ds_read_b128 v[66:69], v133 offset:16384
	ds_read_b128 v[70:73], v133 offset:17408
	ds_read_b128 v[74:77], v134 offset:16384
	ds_read_b128 v[78:81], v134 offset:17408
	ds_read_b128 v[82:85], v137 offset:16384
	ds_read_b128 v[94:97], v137 offset:17408
	ds_read_b128 v[200:203], v139 offset:16384
	ds_read_b128 v[204:207], v139 offset:17408
	s_waitcnt vmcnt(4)
	s_barrier
	s_waitcnt lgkmcnt(0)
	s_setprio 1
	s_waitcnt lgkmcnt(0)
	v_mfma_f32_16x16x32_bf16 v[62:65], v[66:69], v[148:151], v[62:65]
	v_mfma_f32_16x16x32_bf16 v[58:61], v[66:69], v[156:159], v[58:61]
	v_mfma_f32_16x16x32_bf16 v[54:57], v[74:77], v[148:151], v[54:57]
	v_mfma_f32_16x16x32_bf16 v[50:53], v[74:77], v[156:159], v[50:53]
	v_mfma_f32_16x16x32_bf16 v[46:49], v[82:85], v[148:151], v[46:49]
	v_mfma_f32_16x16x32_bf16 v[42:45], v[82:85], v[156:159], v[42:45]
	v_mfma_f32_16x16x32_bf16 v[38:41], v[200:203], v[148:151], v[38:41]
	v_mfma_f32_16x16x32_bf16 v[34:37], v[200:203], v[156:159], v[34:37]
	v_mfma_f32_16x16x32_bf16 v[62:65], v[70:73], v[152:155], v[62:65]
	v_mfma_f32_16x16x32_bf16 v[58:61], v[70:73], v[160:163], v[58:61]
	v_mfma_f32_16x16x32_bf16 v[54:57], v[78:81], v[152:155], v[54:57]
	v_mfma_f32_16x16x32_bf16 v[50:53], v[78:81], v[160:163], v[50:53]
	v_mfma_f32_16x16x32_bf16 v[46:49], v[94:97], v[152:155], v[46:49]
	v_mfma_f32_16x16x32_bf16 v[42:45], v[94:97], v[160:163], v[42:45]
	v_mfma_f32_16x16x32_bf16 v[38:41], v[204:207], v[152:155], v[38:41]
	v_mfma_f32_16x16x32_bf16 v[34:37], v[204:207], v[160:163], v[34:37]
	s_setprio 0
	s_setprio 1
	v_mfma_f32_16x16x32_bf16 v[30:33], v[66:69], v[114:117], v[30:33]
	v_mfma_f32_16x16x32_bf16 v[26:29], v[66:69], v[216:219], v[26:29]
	v_mfma_f32_16x16x32_bf16 v[22:25], v[74:77], v[114:117], v[22:25]
	v_mfma_f32_16x16x32_bf16 v[18:21], v[74:77], v[216:219], v[18:21]
	v_mfma_f32_16x16x32_bf16 v[14:17], v[82:85], v[114:117], v[14:17]
	v_mfma_f32_16x16x32_bf16 v[10:13], v[82:85], v[216:219], v[10:13]
	v_mfma_f32_16x16x32_bf16 v[6:9], v[200:203], v[114:117], v[6:9]
	v_mfma_f32_16x16x32_bf16 v[2:5], v[200:203], v[216:219], v[2:5]
	v_mfma_f32_16x16x32_bf16 v[148:151], v[70:73], v[212:215], v[30:33]
	v_mfma_f32_16x16x32_bf16 v[152:155], v[70:73], v[220:223], v[26:29]
	v_mfma_f32_16x16x32_bf16 v[156:159], v[78:81], v[212:215], v[22:25]
	v_mfma_f32_16x16x32_bf16 v[160:163], v[78:81], v[220:223], v[18:21]
	v_mfma_f32_16x16x32_bf16 v[208:211], v[94:97], v[212:215], v[14:17]
	v_mfma_f32_16x16x32_bf16 v[228:231], v[94:97], v[220:223], v[10:13]
	v_mfma_f32_16x16x32_bf16 v[212:215], v[204:207], v[212:215], v[6:9]
	v_mfma_f32_16x16x32_bf16 v[200:203], v[204:207], v[220:223], v[2:5]
	s_setprio 0
	s_barrier
	ds_read_b128 v[14:17], v145
	ds_read_b128 v[30:33], v145 offset:1024
	ds_read_b128 v[204:207], v145 offset:2048
	ds_read_b128 v[216:219], v145 offset:3072
	ds_read_b128 v[2:5], v133 offset:32768
	ds_read_b128 v[6:9], v133 offset:33792
	ds_read_b128 v[10:13], v134 offset:32768
	ds_read_b128 v[18:21], v134 offset:33792
	ds_read_b128 v[22:25], v137 offset:32768
	ds_read_b128 v[26:29], v137 offset:33792
	ds_read_b128 v[220:223], v139 offset:32768
	ds_read_b128 v[232:235], v139 offset:33792
	s_waitcnt vmcnt(2)
	s_barrier
; #define LDA(dst, b, h) for (int m = 0; m < 4; ++m) for (int k = 0; k < 2; ++k) \
;     dst[m][k] = *reinterpret_cast<const bf16x8*>((char*)SA(b, h) + lds_byte(wr * 64 + m * 16 + fr, k * 32 + fq * 8))
; #define LDB(dst, b, h) for (int n = 0; n < 2; ++n) for (int k = 0; k < 2; ++k) \
;     dst[n][k] = *reinterpret_cast<const bf16x8*>((char*)SB(b, h) + lds_byte(wc * 32 + n * 16 + fr, k * 32 + fq * 8))
; #define MMA(ai, bj, At, Bt_) do { __builtin_amdgcn_s_setprio(1); \
;     for (int m = 0; m < 4; ++m) for (int n = 0; n < 2; ++n) for (int k = 0; k < 2; ++k) \
;       acc[ai][bj][m][n] = __builtin_amdgcn_mfma_f32_16x16x32_bf16(At[m][k], Bt_[n][k], acc[ai][bj][m][n], 0, 0, 0); \
;     __builtin_amdgcn_s_setprio(0); } while (0)
; #define WAIT_V(n) asm volatile("s_waitcnt vmcnt(" #n ")" ::: "memory")
; #define WAIT_L(n) asm volatile("s_waitcnt lgkmcnt(" #n ")" ::: "memory")
; #define BAR __builtin_amdgcn_s_barrier()
;     ...
;     { LDB(B0, 1, 0); LDA(At, 1, 0); WAIT_V(2); BAR; WAIT_L(0); MMA(0, 0, At, B0); BAR;
;       LDB(B1, 1, 1); WAIT_V(0); BAR; WAIT_L(0); MMA(0, 1, At, B1); BAR;
;       LDA(At, 1, 1); BAR; WAIT_L(0); MMA(1, 0, At, B0); MMA(1, 1, At, B1); BAR; }
;     if (wr == 0) BAR;
	s_waitcnt lgkmcnt(0)
	s_setprio 1
	s_waitcnt lgkmcnt(0)
	v_mfma_f32_16x16x32_bf16 v[66:69], v[2:5], v[14:17], v[126:129]
	v_mfma_f32_16x16x32_bf16 v[114:117], v[6:9], v[30:33], v[66:69]
	v_mfma_f32_16x16x32_bf16 v[66:69], v[2:5], v[204:207], v[122:125]
	v_mfma_f32_16x16x32_bf16 v[126:129], v[6:9], v[216:219], v[66:69]
	v_mfma_f32_16x16x32_bf16 v[66:69], v[10:13], v[14:17], v[118:121]
	v_mfma_f32_16x16x32_bf16 v[82:85], v[18:21], v[30:33], v[66:69]
	v_mfma_f32_16x16x32_bf16 v[66:69], v[10:13], v[204:207], v[140:143]
	v_mfma_f32_16x16x32_bf16 v[94:97], v[18:21], v[216:219], v[66:69]
	v_mfma_f32_16x16x32_bf16 v[66:69], v[22:25], v[14:17], v[110:113]
	v_mfma_f32_16x16x32_bf16 v[74:77], v[26:29], v[30:33], v[66:69]
	v_mfma_f32_16x16x32_bf16 v[66:69], v[22:25], v[204:207], v[106:109]
	v_mfma_f32_16x16x32_bf16 v[78:81], v[26:29], v[216:219], v[66:69]
	v_mfma_f32_16x16x32_bf16 v[66:69], v[220:223], v[14:17], v[102:105]
	v_mfma_f32_16x16x32_bf16 v[70:73], v[220:223], v[204:207], v[98:101]
	v_mfma_f32_16x16x32_bf16 v[66:69], v[232:235], v[30:33], v[66:69]
	v_mfma_f32_16x16x32_bf16 v[70:73], v[232:235], v[216:219], v[70:73]
	s_setprio 0
	s_barrier
	ds_read_b128 v[140:143], v146
	ds_read_b128 v[236:239], v146 offset:1024
	ds_read_b128 v[240:243], v146 offset:2048
	ds_read_b128 v[144:147], v146 offset:3072
	s_waitcnt vmcnt(0)
	s_barrier
	s_waitcnt lgkmcnt(0)
	s_setprio 1
	s_waitcnt lgkmcnt(0)
	v_mfma_f32_16x16x32_bf16 v[98:101], v[2:5], v[140:143], v[224:227]
	v_mfma_f32_16x16x32_bf16 v[2:5], v[2:5], v[240:243], v[90:93]
	v_mfma_f32_16x16x32_bf16 v[118:121], v[6:9], v[144:147], v[2:5]
	v_mfma_f32_16x16x32_bf16 v[2:5], v[10:13], v[140:143], v[86:89]
	v_mfma_f32_16x16x32_bf16 v[102:105], v[18:21], v[236:239], v[2:5]
	v_mfma_f32_16x16x32_bf16 v[2:5], v[10:13], v[240:243], v[164:167]
	v_mfma_f32_16x16x32_bf16 v[122:125], v[18:21], v[144:147], v[2:5]
	v_mfma_f32_16x16x32_bf16 v[2:5], v[22:25], v[140:143], v[184:187]
	v_mfma_f32_16x16x32_bf16 v[90:93], v[26:29], v[236:239], v[2:5]
	v_mfma_f32_16x16x32_bf16 v[2:5], v[22:25], v[240:243], v[188:191]
	v_mfma_f32_16x16x32_bf16 v[110:113], v[26:29], v[144:147], v[2:5]
	v_mfma_f32_16x16x32_bf16 v[2:5], v[220:223], v[140:143], v[192:195]
	v_mfma_f32_16x16x32_bf16 v[86:89], v[232:235], v[236:239], v[2:5]
	v_mfma_f32_16x16x32_bf16 v[2:5], v[220:223], v[240:243], v[196:199]
	v_mfma_f32_16x16x32_bf16 v[98:101], v[6:9], v[236:239], v[98:101]
	v_mfma_f32_16x16x32_bf16 v[106:109], v[232:235], v[144:147], v[2:5]
	s_setprio 0
	s_barrier
	ds_read_b128 v[164:167], v133 offset:49152
	ds_read_b128 v[184:187], v133 offset:50176
	ds_read_b128 v[188:191], v134 offset:49152
	ds_read_b128 v[192:195], v134 offset:50176
	ds_read_b128 v[196:199], v137 offset:49152
	ds_read_b128 v[220:223], v137 offset:50176
	ds_read_b128 v[224:227], v139 offset:49152
	ds_read_b128 v[232:235], v139 offset:50176
	s_barrier
	s_waitcnt lgkmcnt(0)
	s_setprio 1
	s_waitcnt lgkmcnt(0)
	v_mfma_f32_16x16x32_bf16 v[6:9], v[164:167], v[204:207], v[58:61]
	v_mfma_f32_16x16x32_bf16 v[10:13], v[188:191], v[204:207], v[50:53]
	v_mfma_f32_16x16x32_bf16 v[2:5], v[164:167], v[14:17], v[62:65]
	v_mfma_f32_16x16x32_bf16 v[18:21], v[184:187], v[216:219], v[6:9]
	v_mfma_f32_16x16x32_bf16 v[6:9], v[188:191], v[14:17], v[54:57]
	v_mfma_f32_16x16x32_bf16 v[22:25], v[192:195], v[216:219], v[10:13]
	v_mfma_f32_16x16x32_bf16 v[10:13], v[196:199], v[14:17], v[46:49]
	v_mfma_f32_16x16x32_bf16 v[14:17], v[224:227], v[14:17], v[38:41]
	v_mfma_f32_16x16x32_bf16 v[2:5], v[184:187], v[30:33], v[2:5]
	v_mfma_f32_16x16x32_bf16 v[6:9], v[192:195], v[30:33], v[6:9]
	v_mfma_f32_16x16x32_bf16 v[10:13], v[220:223], v[30:33], v[10:13]
	v_mfma_f32_16x16x32_bf16 v[26:29], v[196:199], v[204:207], v[42:45]
	v_mfma_f32_16x16x32_bf16 v[14:17], v[232:235], v[30:33], v[14:17]
	v_mfma_f32_16x16x32_bf16 v[30:33], v[224:227], v[204:207], v[34:37]
	v_mfma_f32_16x16x32_bf16 v[26:29], v[220:223], v[216:219], v[26:29]
	v_mfma_f32_16x16x32_bf16 v[30:33], v[232:235], v[216:219], v[30:33]
	s_setprio 0
	s_setprio 1
	v_mfma_f32_16x16x32_bf16 v[38:41], v[164:167], v[240:243], v[152:155]
	v_mfma_f32_16x16x32_bf16 v[42:45], v[188:191], v[240:243], v[160:163]
	v_mfma_f32_16x16x32_bf16 v[46:49], v[196:199], v[240:243], v[228:231]
	v_mfma_f32_16x16x32_bf16 v[34:37], v[164:167], v[140:143], v[148:151]
	v_mfma_f32_16x16x32_bf16 v[50:53], v[184:187], v[144:147], v[38:41]
	v_mfma_f32_16x16x32_bf16 v[38:41], v[188:191], v[140:143], v[156:159]
	v_mfma_f32_16x16x32_bf16 v[54:57], v[192:195], v[144:147], v[42:45]
	v_mfma_f32_16x16x32_bf16 v[42:45], v[196:199], v[140:143], v[208:211]
	v_mfma_f32_16x16x32_bf16 v[58:61], v[220:223], v[144:147], v[46:49]
	v_mfma_f32_16x16x32_bf16 v[46:49], v[224:227], v[140:143], v[212:215]
	v_mfma_f32_16x16x32_bf16 v[62:65], v[224:227], v[240:243], v[200:203]
	v_mfma_f32_16x16x32_bf16 v[34:37], v[184:187], v[236:239], v[34:37]
	v_mfma_f32_16x16x32_bf16 v[38:41], v[192:195], v[236:239], v[38:41]
	v_mfma_f32_16x16x32_bf16 v[42:45], v[220:223], v[236:239], v[42:45]
	v_mfma_f32_16x16x32_bf16 v[46:49], v[232:235], v[236:239], v[46:49]
	v_mfma_f32_16x16x32_bf16 v[62:65], v[232:235], v[144:147], v[62:65]
	s_setprio 0
	v_readlane_b32 s4, v245, 33
	v_readlane_b32 s5, v245, 34
	s_and_b64 vcc, exec, s[4:5]
	s_barrier
	s_cbranch_vccz .LBB0_205
	s_barrier

; #define LDA(dst, b, h) for (int m = 0; m < 4; ++m) for (int k = 0; k < 2; ++k) \
;     dst[m][k] = *reinterpret_cast<const bf16x8*>((char*)SA(b, h) + lds_byte(wr * 64 + m * 16 + fr, k * 32 + fq * 8))
; #define LDB(dst, b, h) for (int n = 0; n < 2; ++n) for (int k = 0; k < 2; ++k) \
;     dst[n][k] = *reinterpret_cast<const bf16x8*>((char*)SB(b, h) + lds_byte(wc * 32 + n * 16 + fr, k * 32 + fq * 8))
; #define MMA(ai, bj, At, Bt_) do { __builtin_amdgcn_s_setprio(1); \
;     for (int m = 0; m < 4; ++m) for (int n = 0; n < 2; ++n) for (int k = 0; k < 2; ++k) \
;       acc[ai][bj][m][n] = __builtin_amdgcn_mfma_f32_16x16x32_bf16(At[m][k], Bt_[n][k], acc[ai][bj][m][n], 0, 0, 0); \
;     __builtin_amdgcn_s_setprio(0); } while (0)
; #define WAIT_L(n) asm volatile("s_waitcnt lgkmcnt(" #n ")" ::: "memory")
; #define BAR __builtin_amdgcn_s_barrier()
; #define SCHED __builtin_amdgcn_sched_barrier(0)
;     ...
;       LDB(B0, 0, 0); SCHED; LDA(At, 0, 0); STAGE(SA(1, 1), A, brow + HALF, t + 1);
;       WAIT_L(8); BAR; WAIT_L(0); MMA(0, 0, At, B0); BAR; SCHED;
;       LDB(B1, 0, 1); STAGE(SB(0, 0), Bt, bcol, t + 2);
;       BAR; WAIT_L(0); MMA(0, 1, At, B1); BAR;
;       LDA(At, 0, 1); STAGE(SA(0, 0), A, brow, t + 2);
;       BAR; WAIT_L(0); MMA(1, 0, At, B0); BAR; SCHED;
.LBB0_418:
	v_add_u32_e32 v143, s2, v142
	ds_read_b128 v[146:149], v143
	ds_read_b128 v[150:153], v143 offset:1024
	ds_read_b128 v[154:157], v143 offset:2048
	ds_read_b128 v[158:161], v143 offset:3072
	s_add_u32 s42, s30, s6
	s_addc_u32 s43, s31, s7
	s_add_u32 s44, s42, 0x80080
	s_addc_u32 s45, s43, 0
	s_add_i32 s41, s15, 0xc000
	ds_read_b128 v[162:165], v133
	ds_read_b128 v[184:187], v133 offset:1024
	ds_read_b128 v[188:191], v134
	ds_read_b128 v[192:195], v134 offset:1024
	ds_read_b128 v[196:199], v137
	ds_read_b128 v[200:203], v137 offset:1024
	ds_read_b128 v[204:207], v139
	ds_read_b128 v[208:211], v139 offset:1024
	s_mov_b32 m0, s41
	v_lshl_add_u64 v[144:145], s[44:45], 0, v[0:1]
	s_add_i32 s37, s15, 0xe000
	global_load_lds_dwordx4 v[144:145], off
	v_lshl_add_u64 v[144:145], s[44:45], 0, v[140:141]
	s_mov_b32 m0, s37
	s_nop 0
	global_load_lds_dwordx4 v[144:145], off
	s_waitcnt lgkmcnt(8)
	s_barrier
	s_waitcnt lgkmcnt(0)
	s_setprio 0
	s_waitcnt lgkmcnt(0)
	v_mfma_f32_16x16x32_bf16 v[126:129], v[162:165], v[146:149], v[126:129]
	v_mfma_f32_16x16x32_bf16 v[122:125], v[162:165], v[154:157], v[122:125]
	v_mfma_f32_16x16x32_bf16 v[118:121], v[188:191], v[146:149], v[118:121]
	v_mfma_f32_16x16x32_bf16 v[114:117], v[188:191], v[154:157], v[114:117]
	v_mfma_f32_16x16x32_bf16 v[110:113], v[196:199], v[146:149], v[110:113]
	v_mfma_f32_16x16x32_bf16 v[106:109], v[196:199], v[154:157], v[106:109]
	v_mfma_f32_16x16x32_bf16 v[102:105], v[204:207], v[146:149], v[102:105]
	v_mfma_f32_16x16x32_bf16 v[98:101], v[204:207], v[154:157], v[98:101]
	v_mfma_f32_16x16x32_bf16 v[126:129], v[184:187], v[150:153], v[126:129]
	v_mfma_f32_16x16x32_bf16 v[122:125], v[184:187], v[158:161], v[122:125]
	v_mfma_f32_16x16x32_bf16 v[118:121], v[192:195], v[150:153], v[118:121]
	v_mfma_f32_16x16x32_bf16 v[114:117], v[192:195], v[158:161], v[114:117]
	v_mfma_f32_16x16x32_bf16 v[110:113], v[200:203], v[150:153], v[110:113]
	v_mfma_f32_16x16x32_bf16 v[106:109], v[200:203], v[158:161], v[106:109]
	v_mfma_f32_16x16x32_bf16 v[102:105], v[208:211], v[150:153], v[102:105]
	v_mfma_f32_16x16x32_bf16 v[98:101], v[208:211], v[158:161], v[98:101]
	s_setprio 1
	s_barrier
	s_add_u32 s44, s34, s6
	s_addc_u32 s45, s35, s7
	s_add_u32 s50, s44, 0x100
	v_add_u32_e32 v144, s76, v142
	s_addc_u32 s51, s45, 0
	s_mov_b32 m0, s23
	ds_read_b128 v[212:215], v144
	ds_read_b128 v[216:219], v144 offset:1024
	ds_read_b128 v[220:223], v144 offset:2048
	ds_read_b128 v[224:227], v144 offset:3072
	s_nop 0
	v_lshl_add_u64 v[166:167], s[50:51], 0, v[0:1]
	global_load_lds_dwordx4 v[166:167], off
	v_lshl_add_u64 v[166:167], s[50:51], 0, v[140:141]
	s_mov_b32 m0, s26
	s_nop 0
	global_load_lds_dwordx4 v[166:167], off
	s_barrier
	s_waitcnt lgkmcnt(0)
	s_setprio 0
	s_waitcnt lgkmcnt(0)
	v_mfma_f32_16x16x32_bf16 v[94:97], v[162:165], v[212:215], v[94:97]
	v_mfma_f32_16x16x32_bf16 v[90:93], v[162:165], v[220:223], v[90:93]
	v_mfma_f32_16x16x32_bf16 v[86:89], v[188:191], v[212:215], v[86:89]
	v_mfma_f32_16x16x32_bf16 v[82:85], v[188:191], v[220:223], v[82:85]
	v_mfma_f32_16x16x32_bf16 v[78:81], v[196:199], v[212:215], v[78:81]
	v_mfma_f32_16x16x32_bf16 v[74:77], v[196:199], v[220:223], v[74:77]
	v_mfma_f32_16x16x32_bf16 v[70:73], v[204:207], v[212:215], v[70:73]
	v_mfma_f32_16x16x32_bf16 v[66:69], v[204:207], v[220:223], v[66:69]
	v_mfma_f32_16x16x32_bf16 v[94:97], v[184:187], v[216:219], v[94:97]
	v_mfma_f32_16x16x32_bf16 v[90:93], v[184:187], v[224:227], v[90:93]
	v_mfma_f32_16x16x32_bf16 v[86:89], v[192:195], v[216:219], v[86:89]
	v_mfma_f32_16x16x32_bf16 v[82:85], v[192:195], v[224:227], v[82:85]
	v_mfma_f32_16x16x32_bf16 v[78:81], v[200:203], v[216:219], v[78:81]
	v_mfma_f32_16x16x32_bf16 v[74:77], v[200:203], v[224:227], v[74:77]
	v_mfma_f32_16x16x32_bf16 v[70:73], v[208:211], v[216:219], v[70:73]
	v_mfma_f32_16x16x32_bf16 v[66:69], v[208:211], v[224:227], v[66:69]
	s_setprio 1
	s_add_u32 s50, s42, 0x100
	s_addc_u32 s51, s43, 0
	s_mov_b32 m0, s15
	s_barrier
	ds_read_b128 v[162:165], v133 offset:16384
	ds_read_b128 v[184:187], v133 offset:17408
	ds_read_b128 v[188:191], v134 offset:16384
	ds_read_b128 v[192:195], v134 offset:17408
	ds_read_b128 v[196:199], v137 offset:16384
	ds_read_b128 v[200:203], v137 offset:17408
	ds_read_b128 v[204:207], v139 offset:16384
	ds_read_b128 v[208:211], v139 offset:17408
	s_nop 0
	v_lshl_add_u64 v[166:167], s[50:51], 0, v[0:1]
	global_load_lds_dwordx4 v[166:167], off
	v_lshl_add_u64 v[166:167], s[50:51], 0, v[140:141]
	s_mov_b32 m0, s25
	s_nop 0
	global_load_lds_dwordx4 v[166:167], off
	s_barrier
	s_waitcnt lgkmcnt(0)
	s_setprio 0
	s_waitcnt lgkmcnt(0)
	v_mfma_f32_16x16x32_bf16 v[62:65], v[162:165], v[146:149], v[62:65]
	v_mfma_f32_16x16x32_bf16 v[58:61], v[162:165], v[154:157], v[58:61]
	v_mfma_f32_16x16x32_bf16 v[54:57], v[188:191], v[146:149], v[54:57]
	v_mfma_f32_16x16x32_bf16 v[50:53], v[188:191], v[154:157], v[50:53]
	v_mfma_f32_16x16x32_bf16 v[46:49], v[196:199], v[146:149], v[46:49]
	v_mfma_f32_16x16x32_bf16 v[42:45], v[196:199], v[154:157], v[42:45]
	v_mfma_f32_16x16x32_bf16 v[38:41], v[204:207], v[146:149], v[38:41]
	v_mfma_f32_16x16x32_bf16 v[34:37], v[204:207], v[154:157], v[34:37]
	v_mfma_f32_16x16x32_bf16 v[62:65], v[184:187], v[150:153], v[62:65]
	v_mfma_f32_16x16x32_bf16 v[58:61], v[184:187], v[158:161], v[58:61]
	v_mfma_f32_16x16x32_bf16 v[54:57], v[192:195], v[150:153], v[54:57]
	v_mfma_f32_16x16x32_bf16 v[50:53], v[192:195], v[158:161], v[50:53]
	v_mfma_f32_16x16x32_bf16 v[46:49], v[200:203], v[150:153], v[46:49]
	v_mfma_f32_16x16x32_bf16 v[42:45], v[200:203], v[158:161], v[42:45]
	v_mfma_f32_16x16x32_bf16 v[38:41], v[208:211], v[150:153], v[38:41]
	v_mfma_f32_16x16x32_bf16 v[34:37], v[208:211], v[158:161], v[34:37]
	s_setprio 1
	s_barrier
; #define LDA(dst, b, h) for (int m = 0; m < 4; ++m) for (int k = 0; k < 2; ++k) \
;     dst[m][k] = *reinterpret_cast<const bf16x8*>((char*)SA(b, h) + lds_byte(wr * 64 + m * 16 + fr, k * 32 + fq * 8))
; #define LDB(dst, b, h) for (int n = 0; n < 2; ++n) for (int k = 0; k < 2; ++k) \
;     dst[n][k] = *reinterpret_cast<const bf16x8*>((char*)SB(b, h) + lds_byte(wc * 32 + n * 16 + fr, k * 32 + fq * 8))
; #define MMA(ai, bj, At, Bt_) do { __builtin_amdgcn_s_setprio(1); \
;     for (int m = 0; m < 4; ++m) for (int n = 0; n < 2; ++n) for (int k = 0; k < 2; ++k) \
;       acc[ai][bj][m][n] = __builtin_amdgcn_mfma_f32_16x16x32_bf16(At[m][k], Bt_[n][k], acc[ai][bj][m][n], 0, 0, 0); \
;     __builtin_amdgcn_s_setprio(0); } while (0)
; #define WAIT_V(n) asm volatile("s_waitcnt vmcnt(" #n ")" ::: "memory")
; #define WAIT_L(n) asm volatile("s_waitcnt lgkmcnt(" #n ")" ::: "memory")
; #define BAR __builtin_amdgcn_s_barrier()
; #define SCHED __builtin_amdgcn_sched_barrier(0)
;     ...
;       STAGE(SB(0, 1), Bt, bcol + HALF, t + 2);
;       WAIT_V(6); BAR; MMA(1, 1, At, B1); BAR;
;       LDB(B0, 1, 0); SCHED; LDA(At, 1, 0); STAGE(SA(0, 1), A, brow + HALF, t + 2);
;       WAIT_L(8); BAR; WAIT_L(0); MMA(0, 0, At, B0); BAR; SCHED;
;       LDB(B1, 1, 1); STAGE(SB(1, 0), Bt, bcol, t + 3);
;       BAR; WAIT_L(0); MMA(0, 1, At, B1); BAR;
;       LDA(At, 1, 1); STAGE(SA(1, 0), A, brow, t + 3);
	s_add_u32 s50, s44, 0x80100
	s_addc_u32 s51, s45, 0
	s_mov_b32 m0, s27
	s_nop 0
	v_lshl_add_u64 v[146:147], s[50:51], 0, v[0:1]
	global_load_lds_dwordx4 v[146:147], off
	v_lshl_add_u64 v[146:147], s[50:51], 0, v[140:141]
	s_mov_b32 m0, s28
	s_nop 0
	global_load_lds_dwordx4 v[146:147], off
	s_waitcnt vmcnt(6)
	s_barrier
	s_setprio 0
	v_mfma_f32_16x16x32_bf16 v[30:33], v[162:165], v[212:215], v[30:33]
	v_mfma_f32_16x16x32_bf16 v[26:29], v[162:165], v[220:223], v[26:29]
	v_mfma_f32_16x16x32_bf16 v[22:25], v[188:191], v[212:215], v[22:25]
	v_mfma_f32_16x16x32_bf16 v[18:21], v[188:191], v[220:223], v[18:21]
	v_mfma_f32_16x16x32_bf16 v[14:17], v[196:199], v[212:215], v[14:17]
	v_mfma_f32_16x16x32_bf16 v[10:13], v[196:199], v[220:223], v[10:13]
	v_mfma_f32_16x16x32_bf16 v[6:9], v[204:207], v[212:215], v[6:9]
	v_mfma_f32_16x16x32_bf16 v[2:5], v[204:207], v[220:223], v[2:5]
	v_mfma_f32_16x16x32_bf16 v[30:33], v[184:187], v[216:219], v[30:33]
	v_mfma_f32_16x16x32_bf16 v[26:29], v[184:187], v[224:227], v[26:29]
	v_mfma_f32_16x16x32_bf16 v[22:25], v[192:195], v[216:219], v[22:25]
	v_mfma_f32_16x16x32_bf16 v[18:21], v[192:195], v[224:227], v[18:21]
	v_mfma_f32_16x16x32_bf16 v[14:17], v[200:203], v[216:219], v[14:17]
	v_mfma_f32_16x16x32_bf16 v[10:13], v[200:203], v[224:227], v[10:13]
	v_mfma_f32_16x16x32_bf16 v[6:9], v[208:211], v[216:219], v[6:9]
	v_mfma_f32_16x16x32_bf16 v[2:5], v[208:211], v[224:227], v[2:5]
	s_setprio 1
	v_add_u32_e32 v145, s77, v142
	s_barrier
	ds_read_b128 v[148:151], v145
	ds_read_b128 v[152:155], v145 offset:1024
	ds_read_b128 v[156:159], v145 offset:2048
	ds_read_b128 v[160:163], v145 offset:3072
	s_add_u32 s50, s42, 0x80100
	s_addc_u32 s51, s43, 0
	s_mov_b32 m0, s17
	ds_read_b128 v[164:167], v133 offset:32768
	ds_read_b128 v[184:187], v133 offset:33792
	ds_read_b128 v[188:191], v134 offset:32768
	ds_read_b128 v[192:195], v134 offset:33792
	ds_read_b128 v[196:199], v137 offset:32768
	ds_read_b128 v[200:203], v137 offset:33792
	ds_read_b128 v[204:207], v139 offset:32768
	ds_read_b128 v[208:211], v139 offset:33792
	s_nop 0
	v_lshl_add_u64 v[146:147], s[50:51], 0, v[0:1]
	global_load_lds_dwordx4 v[146:147], off
	v_lshl_add_u64 v[146:147], s[50:51], 0, v[140:141]
	s_mov_b32 m0, s29
	s_nop 0
	global_load_lds_dwordx4 v[146:147], off
	s_waitcnt lgkmcnt(8)
	s_barrier
	s_waitcnt lgkmcnt(0)
	s_setprio 0
	s_waitcnt lgkmcnt(0)
	v_mfma_f32_16x16x32_bf16 v[126:129], v[164:167], v[148:151], v[126:129]
	v_mfma_f32_16x16x32_bf16 v[122:125], v[164:167], v[156:159], v[122:125]
	v_mfma_f32_16x16x32_bf16 v[118:121], v[188:191], v[148:151], v[118:121]
	v_mfma_f32_16x16x32_bf16 v[114:117], v[188:191], v[156:159], v[114:117]
	v_mfma_f32_16x16x32_bf16 v[110:113], v[196:199], v[148:151], v[110:113]
	v_mfma_f32_16x16x32_bf16 v[106:109], v[196:199], v[156:159], v[106:109]
	v_mfma_f32_16x16x32_bf16 v[102:105], v[204:207], v[148:151], v[102:105]
	v_mfma_f32_16x16x32_bf16 v[98:101], v[204:207], v[156:159], v[98:101]
	v_mfma_f32_16x16x32_bf16 v[126:129], v[184:187], v[152:155], v[126:129]
	v_mfma_f32_16x16x32_bf16 v[122:125], v[184:187], v[160:163], v[122:125]
	v_mfma_f32_16x16x32_bf16 v[118:121], v[192:195], v[152:155], v[118:121]
	v_mfma_f32_16x16x32_bf16 v[114:117], v[192:195], v[160:163], v[114:117]
	v_mfma_f32_16x16x32_bf16 v[110:113], v[200:203], v[152:155], v[110:113]
	v_mfma_f32_16x16x32_bf16 v[106:109], v[200:203], v[160:163], v[106:109]
	v_mfma_f32_16x16x32_bf16 v[102:105], v[208:211], v[152:155], v[102:105]
	v_mfma_f32_16x16x32_bf16 v[98:101], v[208:211], v[160:163], v[98:101]
	s_setprio 1
	s_barrier
	s_add_u32 s50, s44, 0x180
	v_add_u32_e32 v146, s78, v142
	s_addc_u32 s51, s45, 0
	s_mov_b32 m0, s8
	ds_read_b128 v[212:215], v146
	ds_read_b128 v[216:219], v146 offset:1024
	ds_read_b128 v[220:223], v146 offset:2048
	ds_read_b128 v[224:227], v146 offset:3072
	s_nop 0
	v_lshl_add_u64 v[228:229], s[50:51], 0, v[0:1]
	global_load_lds_dwordx4 v[228:229], off
	v_lshl_add_u64 v[228:229], s[50:51], 0, v[140:141]
	s_mov_b32 m0, s9
	s_nop 0
	global_load_lds_dwordx4 v[228:229], off
	s_barrier
	s_waitcnt lgkmcnt(0)
	s_setprio 0
	s_waitcnt lgkmcnt(0)
	v_mfma_f32_16x16x32_bf16 v[94:97], v[164:167], v[212:215], v[94:97]
	v_mfma_f32_16x16x32_bf16 v[90:93], v[164:167], v[220:223], v[90:93]
	v_mfma_f32_16x16x32_bf16 v[86:89], v[188:191], v[212:215], v[86:89]
	v_mfma_f32_16x16x32_bf16 v[82:85], v[188:191], v[220:223], v[82:85]
	v_mfma_f32_16x16x32_bf16 v[78:81], v[196:199], v[212:215], v[78:81]
	v_mfma_f32_16x16x32_bf16 v[74:77], v[196:199], v[220:223], v[74:77]
	v_mfma_f32_16x16x32_bf16 v[70:73], v[204:207], v[212:215], v[70:73]
	v_mfma_f32_16x16x32_bf16 v[66:69], v[204:207], v[220:223], v[66:69]
	v_mfma_f32_16x16x32_bf16 v[94:97], v[184:187], v[216:219], v[94:97]
	v_mfma_f32_16x16x32_bf16 v[90:93], v[184:187], v[224:227], v[90:93]
	v_mfma_f32_16x16x32_bf16 v[86:89], v[192:195], v[216:219], v[86:89]
	v_mfma_f32_16x16x32_bf16 v[82:85], v[192:195], v[224:227], v[82:85]
	v_mfma_f32_16x16x32_bf16 v[78:81], v[200:203], v[216:219], v[78:81]
	v_mfma_f32_16x16x32_bf16 v[74:77], v[200:203], v[224:227], v[74:77]
	v_mfma_f32_16x16x32_bf16 v[70:73], v[208:211], v[216:219], v[70:73]
	v_mfma_f32_16x16x32_bf16 v[66:69], v[208:211], v[224:227], v[66:69]
	s_setprio 1
	s_add_u32 s42, s42, 0x180
	s_addc_u32 s43, s43, 0
	s_mov_b32 m0, s18
	s_barrier
	ds_read_b128 v[164:167], v133 offset:49152
	ds_read_b128 v[184:187], v133 offset:50176
	ds_read_b128 v[188:191], v134 offset:49152
	ds_read_b128 v[192:195], v134 offset:50176
	ds_read_b128 v[196:199], v137 offset:49152
	ds_read_b128 v[200:203], v137 offset:50176
	ds_read_b128 v[204:207], v139 offset:49152
	ds_read_b128 v[208:211], v139 offset:50176
	s_nop 0
	v_lshl_add_u64 v[228:229], s[42:43], 0, v[0:1]
	global_load_lds_dwordx4 v[228:229], off
	v_lshl_add_u64 v[228:229], s[42:43], 0, v[140:141]
	s_mov_b32 m0, s19
	s_nop 0
	global_load_lds_dwordx4 v[228:229], off
	s_barrier
; #define LDA(dst, b, h) for (int m = 0; m < 4; ++m) for (int k = 0; k < 2; ++k) \
;     dst[m][k] = *reinterpret_cast<const bf16x8*>((char*)SA(b, h) + lds_byte(wr * 64 + m * 16 + fr, k * 32 + fq * 8))
; #define LDB(dst, b, h) for (int n = 0; n < 2; ++n) for (int k = 0; k < 2; ++k) \
;     dst[n][k] = *reinterpret_cast<const bf16x8*>((char*)SB(b, h) + lds_byte(wc * 32 + n * 16 + fr, k * 32 + fq * 8))
; #define MMA(ai, bj, At, Bt_) do { __builtin_amdgcn_s_setprio(1); \
;     for (int m = 0; m < 4; ++m) for (int n = 0; n < 2; ++n) for (int k = 0; k < 2; ++k) \
;       acc[ai][bj][m][n] = __builtin_amdgcn_mfma_f32_16x16x32_bf16(At[m][k], Bt_[n][k], acc[ai][bj][m][n], 0, 0, 0); \
;     __builtin_amdgcn_s_setprio(0); } while (0)
; #define WAIT_V(n) asm volatile("s_waitcnt vmcnt(" #n ")" ::: "memory")
; #define WAIT_L(n) asm volatile("s_waitcnt lgkmcnt(" #n ")" ::: "memory")
; #define BAR __builtin_amdgcn_s_barrier()
; #define SCHED __builtin_amdgcn_sched_barrier(0)
;     ...
;       BAR; WAIT_L(0); MMA(1, 0, At, B0); BAR; SCHED;
;       STAGE(SB(1, 1), Bt, bcol + HALF, t + 3);
;       WAIT_V(6); BAR; MMA(1, 1, At, B1); BAR;
;     }
;     { LDB(B0, 0, 0); LDA(At, 0, 0); STAGE(SA(1, 1), A, brow + HALF, nt - 1);
;       BAR; WAIT_L(0); MMA(0, 0, At, B0); BAR;
;       LDB(B1, 0, 1); BAR; WAIT_L(0); MMA(0, 1, At, B1); BAR;
	s_waitcnt lgkmcnt(0)
	s_setprio 0
	s_waitcnt lgkmcnt(0)
	v_mfma_f32_16x16x32_bf16 v[62:65], v[164:167], v[148:151], v[62:65]
	v_mfma_f32_16x16x32_bf16 v[58:61], v[164:167], v[156:159], v[58:61]
	v_mfma_f32_16x16x32_bf16 v[54:57], v[188:191], v[148:151], v[54:57]
	v_mfma_f32_16x16x32_bf16 v[50:53], v[188:191], v[156:159], v[50:53]
	v_mfma_f32_16x16x32_bf16 v[46:49], v[196:199], v[148:151], v[46:49]
	v_mfma_f32_16x16x32_bf16 v[42:45], v[196:199], v[156:159], v[42:45]
	v_mfma_f32_16x16x32_bf16 v[38:41], v[204:207], v[148:151], v[38:41]
	v_mfma_f32_16x16x32_bf16 v[34:37], v[204:207], v[156:159], v[34:37]
	v_mfma_f32_16x16x32_bf16 v[62:65], v[184:187], v[152:155], v[62:65]
	v_mfma_f32_16x16x32_bf16 v[58:61], v[184:187], v[160:163], v[58:61]
	v_mfma_f32_16x16x32_bf16 v[54:57], v[192:195], v[152:155], v[54:57]
	v_mfma_f32_16x16x32_bf16 v[50:53], v[192:195], v[160:163], v[50:53]
	v_mfma_f32_16x16x32_bf16 v[46:49], v[200:203], v[152:155], v[46:49]
	v_mfma_f32_16x16x32_bf16 v[42:45], v[200:203], v[160:163], v[42:45]
	v_mfma_f32_16x16x32_bf16 v[38:41], v[208:211], v[152:155], v[38:41]
	v_mfma_f32_16x16x32_bf16 v[34:37], v[208:211], v[160:163], v[34:37]
	s_setprio 1
	s_barrier
	s_add_u32 s42, s44, 0x80180
	s_addc_u32 s43, s45, 0
	s_mov_b32 m0, s20
	s_nop 0
	v_lshl_add_u64 v[148:149], s[42:43], 0, v[0:1]
	global_load_lds_dwordx4 v[148:149], off
	v_lshl_add_u64 v[148:149], s[42:43], 0, v[140:141]
	s_mov_b32 m0, s21
	s_nop 0
	global_load_lds_dwordx4 v[148:149], off
	s_waitcnt vmcnt(6)
	s_barrier
	s_setprio 0
	v_mfma_f32_16x16x32_bf16 v[30:33], v[164:167], v[212:215], v[30:33]
	v_mfma_f32_16x16x32_bf16 v[26:29], v[164:167], v[220:223], v[26:29]
	v_mfma_f32_16x16x32_bf16 v[22:25], v[188:191], v[212:215], v[22:25]
	v_mfma_f32_16x16x32_bf16 v[18:21], v[188:191], v[220:223], v[18:21]
	v_mfma_f32_16x16x32_bf16 v[14:17], v[196:199], v[212:215], v[14:17]
	v_mfma_f32_16x16x32_bf16 v[10:13], v[196:199], v[220:223], v[10:13]
	v_mfma_f32_16x16x32_bf16 v[6:9], v[204:207], v[212:215], v[6:9]
	v_mfma_f32_16x16x32_bf16 v[2:5], v[204:207], v[220:223], v[2:5]
	v_mfma_f32_16x16x32_bf16 v[30:33], v[184:187], v[216:219], v[30:33]
	v_mfma_f32_16x16x32_bf16 v[26:29], v[184:187], v[224:227], v[26:29]
	v_mfma_f32_16x16x32_bf16 v[22:25], v[192:195], v[216:219], v[22:25]
	v_mfma_f32_16x16x32_bf16 v[18:21], v[192:195], v[224:227], v[18:21]
	v_mfma_f32_16x16x32_bf16 v[14:17], v[200:203], v[216:219], v[14:17]
	v_mfma_f32_16x16x32_bf16 v[10:13], v[200:203], v[224:227], v[10:13]
	v_mfma_f32_16x16x32_bf16 v[6:9], v[208:211], v[216:219], v[6:9]
	v_mfma_f32_16x16x32_bf16 v[2:5], v[208:211], v[224:227], v[2:5]
	s_setprio 1
	s_add_i32 s36, s36, 2
	s_add_u32 s6, s6, 0x100
	s_addc_u32 s7, s7, 0
	s_cmp_gt_u32 s36, 27
	s_barrier
	s_cbranch_scc0 .LBB0_418
	s_setprio 0
	s_add_u32 s4, s4, 0xf80
	s_addc_u32 s5, s5, 0
	s_mov_b32 m0, s41
	ds_read_b128 v[148:151], v143
	ds_read_b128 v[152:155], v143 offset:1024
	ds_read_b128 v[156:159], v143 offset:2048
	ds_read_b128 v[160:163], v143 offset:3072
	ds_read_b128 v[164:167], v133
	ds_read_b128 v[184:187], v133 offset:1024
	ds_read_b128 v[188:191], v134
	ds_read_b128 v[192:195], v134 offset:1024
	ds_read_b128 v[196:199], v137
	ds_read_b128 v[200:203], v137 offset:1024
	ds_read_b128 v[204:207], v139
	ds_read_b128 v[208:211], v139 offset:1024
	s_nop 0
	v_lshl_add_u64 v[142:143], s[4:5], 0, v[0:1]
	global_load_lds_dwordx4 v[142:143], off
	v_lshl_add_u64 v[140:141], s[4:5], 0, v[140:141]
	s_mov_b32 m0, s37
	s_nop 0
	global_load_lds_dwordx4 v[140:141], off
	s_barrier
	s_waitcnt lgkmcnt(0)
	s_setprio 1
	s_waitcnt lgkmcnt(0)
	v_mfma_f32_16x16x32_bf16 v[126:129], v[164:167], v[148:151], v[126:129]
	v_mfma_f32_16x16x32_bf16 v[122:125], v[164:167], v[156:159], v[122:125]
	v_mfma_f32_16x16x32_bf16 v[118:121], v[188:191], v[148:151], v[118:121]
	v_mfma_f32_16x16x32_bf16 v[110:113], v[196:199], v[148:151], v[110:113]
	v_mfma_f32_16x16x32_bf16 v[106:109], v[196:199], v[156:159], v[106:109]
	v_mfma_f32_16x16x32_bf16 v[102:105], v[204:207], v[148:151], v[102:105]
	v_mfma_f32_16x16x32_bf16 v[98:101], v[204:207], v[156:159], v[98:101]
	v_mfma_f32_16x16x32_bf16 v[126:129], v[184:187], v[152:155], v[126:129]
	v_mfma_f32_16x16x32_bf16 v[122:125], v[184:187], v[160:163], v[122:125]
	v_mfma_f32_16x16x32_bf16 v[118:121], v[192:195], v[152:155], v[118:121]
	v_mfma_f32_16x16x32_bf16 v[114:117], v[188:191], v[156:159], v[114:117]
	v_mfma_f32_16x16x32_bf16 v[110:113], v[200:203], v[152:155], v[110:113]
	v_mfma_f32_16x16x32_bf16 v[106:109], v[200:203], v[160:163], v[106:109]
	v_mfma_f32_16x16x32_bf16 v[102:105], v[208:211], v[152:155], v[102:105]
	v_mfma_f32_16x16x32_bf16 v[98:101], v[208:211], v[160:163], v[98:101]
	v_mfma_f32_16x16x32_bf16 v[140:143], v[192:195], v[160:163], v[114:117]
	s_setprio 0
	s_barrier
	s_nop 0
	ds_read_b128 v[114:117], v144
	ds_read_b128 v[212:215], v144 offset:1024
	ds_read_b128 v[216:219], v144 offset:2048
	ds_read_b128 v[220:223], v144 offset:3072
	s_barrier
	s_waitcnt lgkmcnt(0)
	s_setprio 1
	s_waitcnt lgkmcnt(0)
	v_mfma_f32_16x16x32_bf16 v[90:93], v[164:167], v[216:219], v[90:93]
	v_mfma_f32_16x16x32_bf16 v[86:89], v[188:191], v[114:117], v[86:89]
	v_mfma_f32_16x16x32_bf16 v[94:97], v[164:167], v[114:117], v[94:97]
	v_mfma_f32_16x16x32_bf16 v[90:93], v[184:187], v[220:223], v[90:93]
	v_mfma_f32_16x16x32_bf16 v[86:89], v[192:195], v[212:215], v[86:89]
	v_mfma_f32_16x16x32_bf16 v[82:85], v[188:191], v[216:219], v[82:85]
	v_mfma_f32_16x16x32_bf16 v[78:81], v[196:199], v[114:117], v[78:81]
	v_mfma_f32_16x16x32_bf16 v[74:77], v[196:199], v[216:219], v[74:77]
	v_mfma_f32_16x16x32_bf16 v[70:73], v[204:207], v[114:117], v[70:73]
	v_mfma_f32_16x16x32_bf16 v[66:69], v[204:207], v[216:219], v[66:69]
	v_mfma_f32_16x16x32_bf16 v[224:227], v[184:187], v[212:215], v[94:97]
	v_mfma_f32_16x16x32_bf16 v[164:167], v[192:195], v[220:223], v[82:85]
	v_mfma_f32_16x16x32_bf16 v[184:187], v[200:203], v[212:215], v[78:81]
	v_mfma_f32_16x16x32_bf16 v[188:191], v[200:203], v[220:223], v[74:77]
	v_mfma_f32_16x16x32_bf16 v[192:195], v[208:211], v[212:215], v[70:73]
	v_mfma_f32_16x16x32_bf16 v[196:199], v[208:211], v[220:223], v[66:69]
	s_setprio 0
	s_barrier
; #define LDA(dst, b, h) for (int m = 0; m < 4; ++m) for (int k = 0; k < 2; ++k) \
;     dst[m][k] = *reinterpret_cast<const bf16x8*>((char*)SA(b, h) + lds_byte(wr * 64 + m * 16 + fr, k * 32 + fq * 8))
; #define LDB(dst, b, h) for (int n = 0; n < 2; ++n) for (int k = 0; k < 2; ++k) \
;     dst[n][k] = *reinterpret_cast<const bf16x8*>((char*)SB(b, h) + lds_byte(wc * 32 + n * 16 + fr, k * 32 + fq * 8))
; #define MMA(ai, bj, At, Bt_) do { __builtin_amdgcn_s_setprio(1); \
;     for (int m = 0; m < 4; ++m) for (int n = 0; n < 2; ++n) for (int k = 0; k < 2; ++k) \
;       acc[ai][bj][m][n] = __builtin_amdgcn_mfma_f32_16x16x32_bf16(At[m][k], Bt_[n][k], acc[ai][bj][m][n], 0, 0, 0); \
;     __builtin_amdgcn_s_setprio(0); } while (0)
; #define WAIT_V(n) asm volatile("s_waitcnt vmcnt(" #n ")" ::: "memory")
; #define WAIT_L(n) asm volatile("s_waitcnt lgkmcnt(" #n ")" ::: "memory")
; #define BAR __builtin_amdgcn_s_barrier()
;     ...
;       LDA(At, 0, 1); WAIT_V(4); BAR; WAIT_L(0); MMA(1, 0, At, B0); MMA(1, 1, At, B1); BAR; }
;     { LDB(B0, 1, 0); LDA(At, 1, 0); WAIT_V(2); BAR; WAIT_L(0); MMA(0, 0, At, B0); BAR;
	s_nop 0
	ds_read_b128 v[66:69], v133 offset:16384
	ds_read_b128 v[70:73], v133 offset:17408
	ds_read_b128 v[74:77], v134 offset:16384
	ds_read_b128 v[78:81], v134 offset:17408
	ds_read_b128 v[82:85], v137 offset:16384
	ds_read_b128 v[94:97], v137 offset:17408
	ds_read_b128 v[200:203], v139 offset:16384
	ds_read_b128 v[204:207], v139 offset:17408
	s_waitcnt vmcnt(4)
	s_barrier
	s_waitcnt lgkmcnt(0)
	s_setprio 1
	s_waitcnt lgkmcnt(0)
	v_mfma_f32_16x16x32_bf16 v[62:65], v[66:69], v[148:151], v[62:65]
	v_mfma_f32_16x16x32_bf16 v[58:61], v[66:69], v[156:159], v[58:61]
	v_mfma_f32_16x16x32_bf16 v[54:57], v[74:77], v[148:151], v[54:57]
	v_mfma_f32_16x16x32_bf16 v[50:53], v[74:77], v[156:159], v[50:53]
	v_mfma_f32_16x16x32_bf16 v[46:49], v[82:85], v[148:151], v[46:49]
	v_mfma_f32_16x16x32_bf16 v[42:45], v[82:85], v[156:159], v[42:45]
	v_mfma_f32_16x16x32_bf16 v[38:41], v[200:203], v[148:151], v[38:41]
	v_mfma_f32_16x16x32_bf16 v[34:37], v[200:203], v[156:159], v[34:37]
	v_mfma_f32_16x16x32_bf16 v[62:65], v[70:73], v[152:155], v[62:65]
	v_mfma_f32_16x16x32_bf16 v[58:61], v[70:73], v[160:163], v[58:61]
	v_mfma_f32_16x16x32_bf16 v[54:57], v[78:81], v[152:155], v[54:57]
	v_mfma_f32_16x16x32_bf16 v[50:53], v[78:81], v[160:163], v[50:53]
	v_mfma_f32_16x16x32_bf16 v[46:49], v[94:97], v[152:155], v[46:49]
	v_mfma_f32_16x16x32_bf16 v[42:45], v[94:97], v[160:163], v[42:45]
	v_mfma_f32_16x16x32_bf16 v[38:41], v[204:207], v[152:155], v[38:41]
	v_mfma_f32_16x16x32_bf16 v[34:37], v[204:207], v[160:163], v[34:37]
	s_setprio 0
	s_setprio 1
	v_mfma_f32_16x16x32_bf16 v[30:33], v[66:69], v[114:117], v[30:33]
	v_mfma_f32_16x16x32_bf16 v[26:29], v[66:69], v[216:219], v[26:29]
	v_mfma_f32_16x16x32_bf16 v[22:25], v[74:77], v[114:117], v[22:25]
	v_mfma_f32_16x16x32_bf16 v[18:21], v[74:77], v[216:219], v[18:21]
	v_mfma_f32_16x16x32_bf16 v[14:17], v[82:85], v[114:117], v[14:17]
	v_mfma_f32_16x16x32_bf16 v[10:13], v[82:85], v[216:219], v[10:13]
	v_mfma_f32_16x16x32_bf16 v[6:9], v[200:203], v[114:117], v[6:9]
	v_mfma_f32_16x16x32_bf16 v[2:5], v[200:203], v[216:219], v[2:5]
	v_mfma_f32_16x16x32_bf16 v[148:151], v[70:73], v[212:215], v[30:33]
	v_mfma_f32_16x16x32_bf16 v[152:155], v[70:73], v[220:223], v[26:29]
	v_mfma_f32_16x16x32_bf16 v[156:159], v[78:81], v[212:215], v[22:25]
	v_mfma_f32_16x16x32_bf16 v[160:163], v[78:81], v[220:223], v[18:21]
	v_mfma_f32_16x16x32_bf16 v[208:211], v[94:97], v[212:215], v[14:17]
	v_mfma_f32_16x16x32_bf16 v[228:231], v[94:97], v[220:223], v[10:13]
	v_mfma_f32_16x16x32_bf16 v[212:215], v[204:207], v[212:215], v[6:9]
	v_mfma_f32_16x16x32_bf16 v[200:203], v[204:207], v[220:223], v[2:5]
	s_setprio 0
	s_barrier
	ds_read_b128 v[14:17], v145
	ds_read_b128 v[30:33], v145 offset:1024
	ds_read_b128 v[204:207], v145 offset:2048
	ds_read_b128 v[216:219], v145 offset:3072
	ds_read_b128 v[2:5], v133 offset:32768
	ds_read_b128 v[6:9], v133 offset:33792
	ds_read_b128 v[10:13], v134 offset:32768
	ds_read_b128 v[18:21], v134 offset:33792
	ds_read_b128 v[22:25], v137 offset:32768
	ds_read_b128 v[26:29], v137 offset:33792
	ds_read_b128 v[220:223], v139 offset:32768
	ds_read_b128 v[232:235], v139 offset:33792
	s_waitcnt vmcnt(2)
	s_barrier
	s_waitcnt lgkmcnt(0)
	s_setprio 1
	s_waitcnt lgkmcnt(0)
	v_mfma_f32_16x16x32_bf16 v[66:69], v[2:5], v[14:17], v[126:129]
	v_mfma_f32_16x16x32_bf16 v[114:117], v[6:9], v[30:33], v[66:69]
	v_mfma_f32_16x16x32_bf16 v[66:69], v[2:5], v[204:207], v[122:125]
	v_mfma_f32_16x16x32_bf16 v[126:129], v[6:9], v[216:219], v[66:69]
	v_mfma_f32_16x16x32_bf16 v[66:69], v[10:13], v[14:17], v[118:121]
	v_mfma_f32_16x16x32_bf16 v[82:85], v[18:21], v[30:33], v[66:69]
	v_mfma_f32_16x16x32_bf16 v[66:69], v[10:13], v[204:207], v[140:143]
	v_mfma_f32_16x16x32_bf16 v[94:97], v[18:21], v[216:219], v[66:69]
	v_mfma_f32_16x16x32_bf16 v[66:69], v[22:25], v[14:17], v[110:113]
	v_mfma_f32_16x16x32_bf16 v[74:77], v[26:29], v[30:33], v[66:69]
	v_mfma_f32_16x16x32_bf16 v[66:69], v[22:25], v[204:207], v[106:109]
	v_mfma_f32_16x16x32_bf16 v[78:81], v[26:29], v[216:219], v[66:69]
	v_mfma_f32_16x16x32_bf16 v[66:69], v[220:223], v[14:17], v[102:105]
	v_mfma_f32_16x16x32_bf16 v[70:73], v[220:223], v[204:207], v[98:101]
	v_mfma_f32_16x16x32_bf16 v[66:69], v[232:235], v[30:33], v[66:69]
	v_mfma_f32_16x16x32_bf16 v[70:73], v[232:235], v[216:219], v[70:73]
	s_setprio 0
	s_barrier
; #define LDA(dst, b, h) for (int m = 0; m < 4; ++m) for (int k = 0; k < 2; ++k) \
;     dst[m][k] = *reinterpret_cast<const bf16x8*>((char*)SA(b, h) + lds_byte(wr * 64 + m * 16 + fr, k * 32 + fq * 8))
; #define LDB(dst, b, h) for (int n = 0; n < 2; ++n) for (int k = 0; k < 2; ++k) \
;     dst[n][k] = *reinterpret_cast<const bf16x8*>((char*)SB(b, h) + lds_byte(wc * 32 + n * 16 + fr, k * 32 + fq * 8))
; #define MMA(ai, bj, At, Bt_) do { __builtin_amdgcn_s_setprio(1); \
;     for (int m = 0; m < 4; ++m) for (int n = 0; n < 2; ++n) for (int k = 0; k < 2; ++k) \
;       acc[ai][bj][m][n] = __builtin_amdgcn_mfma_f32_16x16x32_bf16(At[m][k], Bt_[n][k], acc[ai][bj][m][n], 0, 0, 0); \
;     __builtin_amdgcn_s_setprio(0); } while (0)
; #define WAIT_V(n) asm volatile("s_waitcnt vmcnt(" #n ")" ::: "memory")
; #define WAIT_L(n) asm volatile("s_waitcnt lgkmcnt(" #n ")" ::: "memory")
; #define BAR __builtin_amdgcn_s_barrier()
;     ...
;       LDB(B1, 1, 1); WAIT_V(0); BAR; WAIT_L(0); MMA(0, 1, At, B1); BAR;
;       LDA(At, 1, 1); BAR; WAIT_L(0); MMA(1, 0, At, B0); MMA(1, 1, At, B1); BAR; }
;     if (wr == 0) BAR;
	ds_read_b128 v[140:143], v146
	ds_read_b128 v[236:239], v146 offset:1024
	ds_read_b128 v[240:243], v146 offset:2048
	ds_read_b128 v[144:147], v146 offset:3072
	s_waitcnt vmcnt(0)
	s_barrier
	s_waitcnt lgkmcnt(0)
	s_setprio 1
	s_waitcnt lgkmcnt(0)
	v_mfma_f32_16x16x32_bf16 v[98:101], v[2:5], v[140:143], v[224:227]
	v_mfma_f32_16x16x32_bf16 v[2:5], v[2:5], v[240:243], v[90:93]
	v_mfma_f32_16x16x32_bf16 v[118:121], v[6:9], v[144:147], v[2:5]
	v_mfma_f32_16x16x32_bf16 v[2:5], v[10:13], v[140:143], v[86:89]
	v_mfma_f32_16x16x32_bf16 v[102:105], v[18:21], v[236:239], v[2:5]
	v_mfma_f32_16x16x32_bf16 v[2:5], v[10:13], v[240:243], v[164:167]
	v_mfma_f32_16x16x32_bf16 v[122:125], v[18:21], v[144:147], v[2:5]
	v_mfma_f32_16x16x32_bf16 v[2:5], v[22:25], v[140:143], v[184:187]
	v_mfma_f32_16x16x32_bf16 v[90:93], v[26:29], v[236:239], v[2:5]
	v_mfma_f32_16x16x32_bf16 v[2:5], v[22:25], v[240:243], v[188:191]
	v_mfma_f32_16x16x32_bf16 v[110:113], v[26:29], v[144:147], v[2:5]
	v_mfma_f32_16x16x32_bf16 v[2:5], v[220:223], v[140:143], v[192:195]
	v_mfma_f32_16x16x32_bf16 v[86:89], v[232:235], v[236:239], v[2:5]
	v_mfma_f32_16x16x32_bf16 v[2:5], v[220:223], v[240:243], v[196:199]
	v_mfma_f32_16x16x32_bf16 v[98:101], v[6:9], v[236:239], v[98:101]
	v_mfma_f32_16x16x32_bf16 v[106:109], v[232:235], v[144:147], v[2:5]
	s_setprio 0
	s_barrier
	ds_read_b128 v[164:167], v133 offset:49152
	ds_read_b128 v[184:187], v133 offset:50176
	ds_read_b128 v[188:191], v134 offset:49152
	ds_read_b128 v[192:195], v134 offset:50176
	ds_read_b128 v[196:199], v137 offset:49152
	ds_read_b128 v[220:223], v137 offset:50176
	ds_read_b128 v[224:227], v139 offset:49152
	ds_read_b128 v[232:235], v139 offset:50176
	s_barrier
	s_waitcnt lgkmcnt(0)
	s_setprio 1
	s_waitcnt lgkmcnt(0)
	v_mfma_f32_16x16x32_bf16 v[6:9], v[164:167], v[204:207], v[58:61]
	v_mfma_f32_16x16x32_bf16 v[10:13], v[188:191], v[204:207], v[50:53]
	v_mfma_f32_16x16x32_bf16 v[2:5], v[164:167], v[14:17], v[62:65]
	v_mfma_f32_16x16x32_bf16 v[18:21], v[184:187], v[216:219], v[6:9]
	v_mfma_f32_16x16x32_bf16 v[6:9], v[188:191], v[14:17], v[54:57]
	v_mfma_f32_16x16x32_bf16 v[22:25], v[192:195], v[216:219], v[10:13]
	v_mfma_f32_16x16x32_bf16 v[10:13], v[196:199], v[14:17], v[46:49]
	v_mfma_f32_16x16x32_bf16 v[14:17], v[224:227], v[14:17], v[38:41]
	v_mfma_f32_16x16x32_bf16 v[2:5], v[184:187], v[30:33], v[2:5]
	v_mfma_f32_16x16x32_bf16 v[6:9], v[192:195], v[30:33], v[6:9]
	v_mfma_f32_16x16x32_bf16 v[10:13], v[220:223], v[30:33], v[10:13]
	v_mfma_f32_16x16x32_bf16 v[26:29], v[196:199], v[204:207], v[42:45]
	v_mfma_f32_16x16x32_bf16 v[14:17], v[232:235], v[30:33], v[14:17]
	v_mfma_f32_16x16x32_bf16 v[30:33], v[224:227], v[204:207], v[34:37]
	v_mfma_f32_16x16x32_bf16 v[26:29], v[220:223], v[216:219], v[26:29]
	v_mfma_f32_16x16x32_bf16 v[30:33], v[232:235], v[216:219], v[30:33]
	s_setprio 0
	s_setprio 1
	v_mfma_f32_16x16x32_bf16 v[38:41], v[164:167], v[240:243], v[152:155]
	v_mfma_f32_16x16x32_bf16 v[42:45], v[188:191], v[240:243], v[160:163]
	v_mfma_f32_16x16x32_bf16 v[46:49], v[196:199], v[240:243], v[228:231]
	v_mfma_f32_16x16x32_bf16 v[34:37], v[164:167], v[140:143], v[148:151]
	v_mfma_f32_16x16x32_bf16 v[50:53], v[184:187], v[144:147], v[38:41]
	v_mfma_f32_16x16x32_bf16 v[38:41], v[188:191], v[140:143], v[156:159]
	v_mfma_f32_16x16x32_bf16 v[54:57], v[192:195], v[144:147], v[42:45]
	v_mfma_f32_16x16x32_bf16 v[42:45], v[196:199], v[140:143], v[208:211]
	v_mfma_f32_16x16x32_bf16 v[58:61], v[220:223], v[144:147], v[46:49]
	v_mfma_f32_16x16x32_bf16 v[46:49], v[224:227], v[140:143], v[212:215]
	v_mfma_f32_16x16x32_bf16 v[62:65], v[224:227], v[240:243], v[200:203]
	v_mfma_f32_16x16x32_bf16 v[34:37], v[184:187], v[236:239], v[34:37]
	v_mfma_f32_16x16x32_bf16 v[38:41], v[192:195], v[236:239], v[38:41]
	v_mfma_f32_16x16x32_bf16 v[42:45], v[220:223], v[236:239], v[42:45]
	v_mfma_f32_16x16x32_bf16 v[46:49], v[232:235], v[236:239], v[46:49]
	v_mfma_f32_16x16x32_bf16 v[62:65], v[232:235], v[144:147], v[62:65]
	s_setprio 0
	v_readlane_b32 s4, v245, 33
	v_readlane_b32 s5, v245, 34
	s_and_b64 vcc, exec, s[4:5]
	s_barrier
	s_cbranch_vccz .LBB0_421
	s_barrier
